# xor-butterfly reductions via ds_bpermute replaced by DPP/permlane-swap VALU ops (norm_gif gate dots + row norm, attention epilogue ssq), norm weights preloaded in norm_gif; on top of rope pipelining
# speedup vs baseline: 1.0069x; 1.0069x over previous
.LBB0_299:
	s_andn2_b64 vcc, exec, s[0:1]
	s_waitcnt lgkmcnt(0)
	s_barrier
	s_cbranch_vccnz .LBB0_266
	ds_read2st64_b32 v[4:5], v143 offset1:1
	ds_read2st64_b32 v[12:13], v143 offset0:2 offset1:3
	ds_read2st64_b32 v[14:15], v143 offset0:4 offset1:5
	ds_read2st64_b32 v[16:17], v143 offset0:6 offset1:7
	s_lshl_b32 s0, s36, 6
	s_and_b32 s4, s0, 0x2000
	s_waitcnt lgkmcnt(2)
	v_sub_f32_e32 v7, v135, v12
	v_sub_f32_e32 v112, v0, v4
	v_sub_f32_e32 v10, v134, v5
	v_sub_f32_e32 v5, v136, v13
	s_waitcnt lgkmcnt(1)
	v_sub_f32_e32 v4, v2, v14
	v_sub_f32_e32 v2, v20, v15
	s_waitcnt lgkmcnt(0)
	v_sub_f32_e32 v0, v21, v16
	ds_read2st64_b32 v[12:13], v143 offset0:8 offset1:9
	v_sub_f32_e32 v3, v3, v17
	ds_read2st64_b32 v[16:17], v143 offset0:10 offset1:11
	ds_read2st64_b32 v[20:21], v143 offset0:12 offset1:13
	ds_read2st64_b32 v[30:31], v143 offset0:14 offset1:15
	s_waitcnt lgkmcnt(3)
	v_sub_f32_e32 v15, v6, v12
	v_sub_f32_e32 v14, v8, v13
	s_waitcnt lgkmcnt(2)
	v_sub_f32_e32 v13, v9, v16
	v_sub_f32_e32 v12, v22, v17
	s_waitcnt lgkmcnt(1)
	v_sub_f32_e32 v8, v28, v21
	s_waitcnt lgkmcnt(0)
	v_sub_f32_e32 v6, v29, v30
	ds_read2st64_b32 v[16:17], v143 offset0:16 offset1:17
	v_sub_f32_e32 v9, v23, v31
	ds_read2st64_b32 v[28:29], v143 offset0:18 offset1:19
	ds_read2st64_b32 v[30:31], v143 offset0:20 offset1:21
	ds_read2st64_b32 v[32:33], v143 offset0:22 offset1:23
	v_sub_f32_e32 v11, v11, v20
	s_waitcnt lgkmcnt(3)
	v_sub_f32_e32 v22, v133, v16
	v_sub_f32_e32 v23, v132, v17
	s_waitcnt lgkmcnt(2)
	v_sub_f32_e32 v21, v131, v28
	v_sub_f32_e32 v20, v130, v29
	s_waitcnt lgkmcnt(0)
	v_sub_f32_e32 v16, v35, v32
	v_sub_f32_e32 v17, v34, v33
	ds_read2st64_b32 v[28:29], v143 offset0:24 offset1:25
	ds_read2st64_b32 v[32:33], v143 offset0:26 offset1:27
	ds_read2st64_b32 v[34:35], v143 offset0:28 offset1:29
	ds_read2st64_b32 v[46:47], v143 offset0:30 offset1:31
	v_sub_f32_e32 v19, v19, v30
	v_sub_f32_e32 v18, v18, v31
	v_mul_f32_e32 v151, v22, v22
	s_waitcnt lgkmcnt(3)
	v_sub_f32_e32 v31, v39, v28
	v_sub_f32_e32 v30, v38, v29
	s_waitcnt lgkmcnt(2)
	v_sub_f32_e32 v29, v25, v32
	v_sub_f32_e32 v28, v24, v33
	s_waitcnt lgkmcnt(1)
	v_sub_f32_e32 v27, v27, v34
	v_sub_f32_e32 v26, v26, v35
	s_waitcnt lgkmcnt(0)
	v_sub_f32_e32 v24, v43, v46
	v_sub_f32_e32 v25, v42, v47
	ds_read2st64_b32 v[32:33], v143 offset0:32 offset1:33
	ds_read2st64_b32 v[34:35], v143 offset0:34 offset1:35
	ds_read2st64_b32 v[38:39], v143 offset0:36 offset1:37
	ds_read2st64_b32 v[42:43], v143 offset0:38 offset1:39
	v_fmac_f32_e32 v151, v112, v112
	v_mul_f32_e32 v148, v23, v23
	v_fmac_f32_e32 v148, v10, v10
	s_waitcnt lgkmcnt(1)
	v_sub_f32_e32 v36, v36, v38
	v_sub_f32_e32 v37, v37, v39
	s_waitcnt lgkmcnt(0)
	v_sub_f32_e32 v38, v53, v42
	v_sub_f32_e32 v39, v52, v43
	ds_read2st64_b32 v[42:43], v143 offset0:40 offset1:41
	ds_read2st64_b32 v[46:47], v143 offset0:42 offset1:43
	ds_read2st64_b32 v[48:49], v143 offset0:44 offset1:45
	ds_read2st64_b32 v[52:53], v143 offset0:46 offset1:47
	v_sub_f32_e32 v32, v161, v32
	v_fmac_f32_e32 v151, v32, v32
	v_sub_f32_e32 v33, v160, v33
	s_waitcnt lgkmcnt(3)
	v_sub_f32_e32 v40, v40, v42
	v_sub_f32_e32 v41, v41, v43
	s_waitcnt lgkmcnt(2)
	v_sub_f32_e32 v42, v55, v46
	v_sub_f32_e32 v43, v54, v47
	s_waitcnt lgkmcnt(1)
	v_sub_f32_e32 v44, v44, v48
	v_sub_f32_e32 v45, v45, v49
	s_waitcnt lgkmcnt(0)
	v_sub_f32_e32 v46, v61, v52
	v_sub_f32_e32 v47, v60, v53
	ds_read2st64_b32 v[48:49], v143 offset0:48 offset1:49
	ds_read2st64_b32 v[60:61], v143 offset0:50 offset1:51
	ds_read2st64_b32 v[62:63], v143 offset0:52 offset1:53
	ds_read2st64_b32 v[64:65], v143 offset0:54 offset1:55
	v_fmac_f32_e32 v148, v33, v33
	v_mul_f32_e32 v144, v21, v21
	s_waitcnt lgkmcnt(2)
	v_sub_f32_e32 v53, v153, v60
	v_sub_f32_e32 v55, v155, v48
	v_sub_f32_e32 v54, v154, v49
	v_sub_f32_e32 v52, v152, v61
	s_waitcnt lgkmcnt(0)
	v_sub_f32_e32 v48, v87, v64
	v_sub_f32_e32 v49, v86, v65
	ds_read2st64_b32 v[60:61], v143 offset0:56 offset1:57
	ds_read2st64_b32 v[64:65], v143 offset0:58 offset1:59
	ds_read2st64_b32 v[86:87], v143 offset0:60 offset1:61
	ds_read2st64_b32 v[152:153], v143 offset0:62 offset1:63
	v_sub_f32_e32 v51, v51, v62
	v_sub_f32_e32 v50, v50, v63
	v_fmac_f32_e32 v151, v55, v55
	s_waitcnt lgkmcnt(3)
	v_sub_f32_e32 v63, v157, v60
	v_sub_f32_e32 v62, v156, v61
	s_waitcnt lgkmcnt(2)
	v_sub_f32_e32 v61, v57, v64
	v_sub_f32_e32 v60, v56, v65
	s_waitcnt lgkmcnt(1)
	v_sub_f32_e32 v59, v59, v86
	v_sub_f32_e32 v58, v58, v87
	s_waitcnt lgkmcnt(0)
	v_sub_f32_e32 v56, v95, v152
	v_sub_f32_e32 v57, v94, v153
	ds_read2st64_b32 v[64:65], v143 offset0:64 offset1:65
	ds_read2st64_b32 v[86:87], v143 offset0:66 offset1:67
	ds_read2st64_b32 v[94:95], v143 offset0:68 offset1:69
	ds_read2st64_b32 v[152:153], v143 offset0:70 offset1:71
	v_fmac_f32_e32 v148, v54, v54
	v_fmac_f32_e32 v144, v7, v7
	s_waitcnt lgkmcnt(2)
	v_sub_f32_e32 v66, v66, v86
	v_sub_f32_e32 v64, v69, v64
	v_sub_f32_e32 v65, v68, v65
	v_sub_f32_e32 v67, v67, v87
	s_waitcnt lgkmcnt(1)
	v_sub_f32_e32 v68, v73, v94
	v_sub_f32_e32 v69, v72, v95
	s_waitcnt lgkmcnt(0)
	v_sub_f32_e32 v70, v70, v152
	v_sub_f32_e32 v71, v71, v153
	ds_read2st64_b32 v[72:73], v143 offset0:72 offset1:73
	ds_read2st64_b32 v[86:87], v143 offset0:74 offset1:75
	ds_read2st64_b32 v[94:95], v143 offset0:76 offset1:77
	ds_read2st64_b32 v[152:153], v143 offset0:78 offset1:79
	v_fmac_f32_e32 v151, v64, v64
	v_fmac_f32_e32 v148, v65, v65
	s_waitcnt lgkmcnt(2)
	v_sub_f32_e32 v74, v74, v86
	v_sub_f32_e32 v72, v77, v72
	v_sub_f32_e32 v73, v76, v73
	s_waitcnt lgkmcnt(1)
	v_sub_f32_e32 v76, v81, v94
	v_sub_f32_e32 v77, v80, v95
	s_waitcnt lgkmcnt(0)
	v_sub_f32_e32 v78, v78, v152
	v_sub_f32_e32 v79, v79, v153
	ds_read2st64_b32 v[80:81], v143 offset0:80 offset1:81
	ds_read2st64_b32 v[94:95], v143 offset0:82 offset1:83
	ds_read2st64_b32 v[152:153], v143 offset0:84 offset1:85
	ds_read2st64_b32 v[154:155], v143 offset0:86 offset1:87
	v_sub_f32_e32 v75, v75, v87
	v_sub_f32_e32 v34, v159, v34
	v_fmac_f32_e32 v144, v34, v34
	s_waitcnt lgkmcnt(3)
	v_sub_f32_e32 v87, v85, v80
	v_sub_f32_e32 v86, v84, v81
	s_waitcnt lgkmcnt(2)
	v_sub_f32_e32 v85, v83, v94
	v_sub_f32_e32 v84, v82, v95
	s_waitcnt lgkmcnt(1)
	v_sub_f32_e32 v83, v147, v152
	v_sub_f32_e32 v82, v146, v153
	s_waitcnt lgkmcnt(0)
	v_sub_f32_e32 v80, v89, v154
	v_sub_f32_e32 v81, v88, v155
	ds_read2st64_b32 v[88:89], v143 offset0:88 offset1:89
	ds_read2st64_b32 v[146:147], v143 offset0:90 offset1:91
	ds_read2st64_b32 v[152:153], v143 offset0:92 offset1:93
	ds_read2st64_b32 v[154:155], v143 offset0:94 offset1:95
	v_fmac_f32_e32 v151, v87, v87
	v_fmac_f32_e32 v148, v86, v86
	v_fmac_f32_e32 v144, v53, v53
	s_waitcnt lgkmcnt(3)
	v_sub_f32_e32 v95, v93, v88
	v_sub_f32_e32 v94, v92, v89
	s_waitcnt lgkmcnt(2)
	v_sub_f32_e32 v93, v91, v146
	v_sub_f32_e32 v92, v90, v147
	s_waitcnt lgkmcnt(1)
	v_sub_f32_e32 v91, v150, v152
	v_sub_f32_e32 v90, v149, v153
	s_waitcnt lgkmcnt(0)
	v_sub_f32_e32 v88, v97, v154
	v_sub_f32_e32 v89, v96, v155
	ds_read2st64_b32 v[96:97], v143 offset0:96 offset1:97
	ds_read2st64_b32 v[146:147], v143 offset0:98 offset1:99
	ds_read2st64_b32 v[152:153], v143 offset0:100 offset1:101
	ds_read2st64_b32 v[154:155], v143 offset0:102 offset1:103
	v_fmac_f32_e32 v144, v66, v66
	v_fmac_f32_e32 v144, v85, v85
	s_waitcnt lgkmcnt(2)
	v_sub_f32_e32 v98, v98, v146
	v_sub_f32_e32 v96, v101, v96
	v_sub_f32_e32 v97, v100, v97
	v_sub_f32_e32 v99, v99, v147
	s_waitcnt lgkmcnt(1)
	v_sub_f32_e32 v100, v105, v152
	v_sub_f32_e32 v101, v104, v153
	s_waitcnt lgkmcnt(0)
	v_sub_f32_e32 v102, v102, v154
	v_sub_f32_e32 v103, v103, v155
	ds_read2st64_b32 v[104:105], v143 offset0:104 offset1:105
	ds_read2st64_b32 v[146:147], v143 offset0:106 offset1:107
	ds_read2st64_b32 v[152:153], v143 offset0:108 offset1:109
	ds_read2st64_b32 v[154:155], v143 offset0:110 offset1:111
	v_fmac_f32_e32 v151, v96, v96
	v_fmac_f32_e32 v148, v97, v97
	s_waitcnt lgkmcnt(2)
	v_sub_f32_e32 v106, v106, v146
	v_sub_f32_e32 v107, v107, v147
	ds_read2st64_b32 v[146:147], v143 offset0:112 offset1:113
	v_sub_f32_e32 v104, v109, v104
	v_sub_f32_e32 v105, v108, v105
	s_waitcnt lgkmcnt(2)
	v_sub_f32_e32 v108, v145, v152
	v_sub_f32_e32 v109, v113, v153
	s_waitcnt lgkmcnt(1)
	v_sub_f32_e32 v110, v110, v154
	v_sub_f32_e32 v111, v111, v155
	ds_read2st64_b32 v[152:153], v143 offset0:114 offset1:115
	ds_read2st64_b32 v[154:155], v143 offset0:116 offset1:117
	ds_read2st64_b32 v[156:157], v143 offset0:118 offset1:119
	s_waitcnt lgkmcnt(3)
	v_sub_f32_e32 v117, v117, v146
	v_fmac_f32_e32 v151, v117, v117
	v_sub_f32_e32 v116, v116, v147
	s_waitcnt lgkmcnt(1)
	v_sub_f32_e32 v113, v121, v154
	ds_read2st64_b32 v[146:147], v143 offset0:120 offset1:121
	v_sub_f32_e32 v115, v115, v152
	v_sub_f32_e32 v114, v114, v153
	v_sub_f32_e32 v119, v119, v155
	s_waitcnt lgkmcnt(1)
	s_nop 1
	v_add_f32_dpp v121, v151, v151 quad_perm:[1,0,3,2] row_mask:0xf bank_mask:0xf
	ds_read2st64_b32 v[150:151], v143 offset0:122 offset1:123
	ds_read2st64_b32 v[152:153], v143 offset0:124 offset1:125
	ds_read2st64_b32 v[154:155], v143 offset0:126 offset1:127
	v_fmac_f32_e32 v148, v116, v116
	s_waitcnt lgkmcnt(4)
	v_sub_f32_e32 v124, v124, v147
	s_waitcnt lgkmcnt(4)
	s_nop 1
	v_add_f32_dpp v145, v121, v121 quad_perm:[2,3,0,1] row_mask:0xf bank_mask:0xf
	v_sub_f32_e32 v121, v125, v146
	v_fmac_f32_e32 v144, v98, v98
	s_waitcnt lgkmcnt(1)
	s_nop 1
	v_add_f32_dpp v147, v148, v148 quad_perm:[1,0,3,2] row_mask:0xf bank_mask:0xf
	s_waitcnt lgkmcnt(1)
	s_nop 1
	v_add_f32_dpp v125, v145, v145 row_half_mirror row_mask:0xf bank_mask:0xf
	v_fmac_f32_e32 v144, v115, v115
	v_sub_f32_e32 v122, v122, v150
	v_mul_f32_e32 v131, v20, v20
	v_fmac_f32_e32 v131, v5, v5
	s_waitcnt lgkmcnt(0)
	s_nop 1
	v_add_f32_dpp v143, v125, v125 row_mirror row_mask:0xf bank_mask:0xf
	v_sub_f32_e32 v125, v123, v151
	v_sub_f32_e32 v123, v129, v152
	v_sub_f32_e32 v35, v158, v35
	s_waitcnt lgkmcnt(1)
	v_mov_b32_e32 v129, v143
	v_mov_b32_e32 v145, v143
	s_nop 1
	v_permlane16_swap_b32_e32 v129, v145
	v_add_f32_e32 v129, v129, v145
	v_fmamk_f32 v129, v129, 0x3b800000, v244
	v_mul_f32_e32 v143, 0x4f800000, v129
	v_cmp_gt_f32_e32 vcc, s25, v129
	s_waitcnt lgkmcnt(0)
	s_nop 1
	v_add_f32_dpp v144, v144, v144 quad_perm:[1,0,3,2] row_mask:0xf bank_mask:0xf
	v_cndmask_b32_e32 v129, v129, v143, vcc
	v_sqrt_f32_e32 v143, v129
	v_fmac_f32_e32 v131, v35, v35
	v_fmac_f32_e32 v131, v52, v52
	s_waitcnt lgkmcnt(0)
	s_nop 1
	v_add_f32_dpp v144, v144, v144 quad_perm:[2,3,0,1] row_mask:0xf bank_mask:0xf
	v_add_u32_e32 v145, -1, v143
	v_fma_f32 v146, -v145, v143, v129
	v_cmp_ge_f32_e64 s[0:1], 0, v146
	v_add_u32_e32 v146, 1, v143
	v_fmac_f32_e32 v131, v67, v67
	v_cndmask_b32_e64 v145, v143, v145, s[0:1]
	v_fma_f32 v143, -v146, v143, v129
	v_cmp_lt_f32_e64 s[0:1], 0, v143
	v_fmac_f32_e32 v131, v84, v84
	v_fmac_f32_e32 v131, v99, v99
	v_cndmask_b32_e64 v143, v145, v146, s[0:1]
	v_mul_f32_e32 v145, 0x37800000, v143
	v_cndmask_b32_e32 v143, v143, v145, vcc
	s_nop 1
	v_add_f32_dpp v145, v147, v147 quad_perm:[2,3,0,1] row_mask:0xf bank_mask:0xf
	v_cmp_class_f32_e32 vcc, v129, v245
	v_fmac_f32_e32 v131, v114, v114
	v_cndmask_b32_e32 v129, v143, v129, vcc
	s_waitcnt lgkmcnt(1)
	s_nop 1
	v_add_f32_dpp v145, v145, v145 row_half_mirror row_mask:0xf bank_mask:0xf
	v_div_scale_f32 v143, s[0:1], v129, v129, s26
	v_rcp_f32_e32 v147, v143
	s_waitcnt lgkmcnt(1)
	s_nop 1
	v_add_f32_dpp v131, v131, v131 quad_perm:[1,0,3,2] row_mask:0xf bank_mask:0xf
	s_waitcnt lgkmcnt(0)
	s_nop 1
	v_add_f32_dpp v145, v145, v145 row_mirror row_mask:0xf bank_mask:0xf
	v_fma_f32 v148, -v143, v147, 1.0
	v_fmac_f32_e32 v147, v148, v147
	v_div_scale_f32 v148, vcc, s26, v129, s26
	s_waitcnt lgkmcnt(0)
	v_mov_b32_e32 v146, v145
	s_nop 1
	v_permlane16_swap_b32_e32 v145, v146
	v_add_f32_e32 v145, v145, v146
	v_fmamk_f32 v145, v145, 0x3b800000, v244
	v_mul_f32_e32 v146, 0x4f800000, v145
	v_cmp_gt_f32_e64 s[0:1], s25, v145
	v_mul_f32_e32 v149, v148, v147
	v_fma_f32 v150, -v143, v149, v148
	v_cndmask_b32_e64 v145, v145, v146, s[0:1]
	v_sqrt_f32_e32 v146, v145
	v_fmac_f32_e32 v149, v150, v147
	v_fma_f32 v143, -v143, v149, v148
	v_div_fmas_f32 v143, v143, v147, v149
	v_add_u32_e32 v148, -1, v146
	v_fma_f32 v150, -v148, v146, v145
	v_cmp_ge_f32_e64 s[2:3], 0, v150
	v_add_u32_e32 v150, 1, v146
	v_div_fixup_f32 v129, v143, v129, s26
	v_cndmask_b32_e64 v148, v146, v148, s[2:3]
	v_fma_f32 v146, -v150, v146, v145
	v_cmp_lt_f32_e64 s[2:3], 0, v146
	v_mul_f32_e32 v133, v19, v19
	v_cndmask_b32_e64 v146, v148, v150, s[2:3]
	v_mul_f32_e32 v148, 0x37800000, v146
	v_cndmask_b32_e64 v146, v146, v148, s[0:1]
	v_cmp_class_f32_e64 s[0:1], v145, v245
	s_waitcnt lgkmcnt(1)
	s_nop 1
	v_add_f32_dpp v131, v131, v131 quad_perm:[2,3,0,1] row_mask:0xf bank_mask:0xf
	v_fmac_f32_e32 v133, v4, v4
	v_cndmask_b32_e64 v145, v146, v145, s[0:1]
	s_waitcnt lgkmcnt(0)
	s_nop 1
	v_add_f32_dpp v144, v144, v144 row_half_mirror row_mask:0xf bank_mask:0xf
	v_div_scale_f32 v146, s[0:1], v145, v145, s26
	v_rcp_f32_e32 v150, v146
	v_fmac_f32_e32 v133, v36, v36
	s_waitcnt lgkmcnt(0)
	s_nop 1
	v_add_f32_dpp v144, v144, v144 row_mirror row_mask:0xf bank_mask:0xf
	v_fma_f32 v143, -v146, v150, 1.0
	v_fmac_f32_e32 v150, v143, v150
	v_div_scale_f32 v143, vcc, s26, v145, s26
	s_waitcnt lgkmcnt(0)
	v_mov_b32_e32 v147, v144
	s_nop 1
	v_permlane16_swap_b32_e32 v144, v147
	v_add_f32_e32 v144, v144, v147
	v_fmamk_f32 v144, v144, 0x3b800000, v244
	v_mul_f32_e32 v147, 0x4f800000, v144
	v_cmp_gt_f32_e64 s[0:1], s25, v144
	v_mul_f32_e32 v148, v143, v150
	v_fma_f32 v149, -v146, v148, v143
	v_cndmask_b32_e64 v144, v144, v147, s[0:1]
	v_sqrt_f32_e32 v147, v144
	v_fmac_f32_e32 v148, v149, v150
	v_fma_f32 v143, -v146, v148, v143
	v_fmac_f32_e32 v133, v51, v51
	v_add_u32_e32 v146, -1, v147
	v_fma_f32 v149, -v146, v147, v144
	v_cmp_ge_f32_e64 s[2:3], 0, v149
	v_add_u32_e32 v149, 1, v147
	v_fmac_f32_e32 v133, v68, v68
	v_cndmask_b32_e64 v146, v147, v146, s[2:3]
	v_fma_f32 v147, -v149, v147, v144
	v_cmp_lt_f32_e64 s[2:3], 0, v147
	v_fmac_f32_e32 v133, v83, v83
	v_fmac_f32_e32 v133, v100, v100
	v_cndmask_b32_e64 v146, v146, v149, s[2:3]
	v_mul_f32_e32 v147, 0x37800000, v146
	v_cndmask_b32_e64 v146, v146, v147, s[0:1]
	v_cmp_class_f32_e64 s[0:1], v144, v245
	v_fmac_f32_e32 v133, v113, v113
	v_mul_f32_e32 v135, v18, v18
	v_cndmask_b32_e64 v144, v146, v144, s[0:1]
	s_waitcnt lgkmcnt(0)
	s_nop 1
	v_add_f32_dpp v147, v131, v131 row_half_mirror row_mask:0xf bank_mask:0xf
	v_div_fmas_f32 v131, v143, v150, v148
	v_div_fixup_f32 v131, v131, v145, s26
	v_div_scale_f32 v146, s[0:1], v144, v144, s26
	s_waitcnt lgkmcnt(0)
	s_nop 1
	v_add_f32_dpp v145, v147, v147 row_mirror row_mask:0xf bank_mask:0xf
	v_rcp_f32_e32 v149, v146
	v_fmac_f32_e32 v135, v2, v2
	v_fmac_f32_e32 v135, v37, v37
	s_waitcnt lgkmcnt(1)
	v_mov_b32_e32 v147, v145
	s_nop 1
	v_permlane16_swap_b32_e32 v145, v147
	v_add_f32_e32 v145, v145, v147
	v_fmamk_f32 v145, v145, 0x3b800000, v244
	v_mul_f32_e32 v147, 0x4f800000, v145
	v_cmp_gt_f32_e64 s[0:1], s25, v145
	v_fma_f32 v143, -v146, v149, 1.0
	v_fmac_f32_e32 v149, v143, v149
	v_cndmask_b32_e64 v145, v145, v147, s[0:1]
	v_div_scale_f32 v143, vcc, s26, v144, s26
	v_sqrt_f32_e32 v147, v145
	v_mul_f32_e32 v148, v143, v149
	v_fma_f32 v150, -v146, v148, v143
	v_fmac_f32_e32 v148, v150, v149
	v_fma_f32 v143, -v146, v148, v143
	v_add_u32_e32 v146, -1, v147
	s_waitcnt lgkmcnt(0)
	s_nop 1
	v_add_f32_dpp v133, v133, v133 quad_perm:[1,0,3,2] row_mask:0xf bank_mask:0xf
	v_fma_f32 v150, -v146, v147, v145
	v_cmp_ge_f32_e64 s[2:3], 0, v150
	v_add_u32_e32 v150, 1, v147
	v_fmac_f32_e32 v135, v50, v50
	v_cndmask_b32_e64 v146, v147, v146, s[2:3]
	v_fma_f32 v147, -v150, v147, v145
	v_cmp_lt_f32_e64 s[2:3], 0, v147
	s_waitcnt lgkmcnt(0)
	s_nop 1
	v_add_f32_dpp v133, v133, v133 quad_perm:[2,3,0,1] row_mask:0xf bank_mask:0xf
	v_fmac_f32_e32 v135, v69, v69
	v_cndmask_b32_e64 v146, v146, v150, s[2:3]
	v_mul_f32_e32 v147, 0x37800000, v146
	v_cndmask_b32_e64 v146, v146, v147, s[0:1]
	v_cmp_class_f32_e64 s[0:1], v145, v245
	v_fmac_f32_e32 v135, v82, v82
	v_fmac_f32_e32 v135, v101, v101
	v_cndmask_b32_e64 v145, v146, v145, s[0:1]
	s_waitcnt lgkmcnt(0)
	s_nop 1
	v_add_f32_dpp v147, v133, v133 row_half_mirror row_mask:0xf bank_mask:0xf
	v_div_fmas_f32 v133, v143, v149, v148
	v_div_fixup_f32 v133, v133, v144, s26
	v_div_scale_f32 v146, s[0:1], v145, v145, s26
	s_waitcnt lgkmcnt(0)
	s_nop 1
	v_add_f32_dpp v144, v147, v147 row_mirror row_mask:0xf bank_mask:0xf
	v_rcp_f32_e32 v150, v146
	v_fmac_f32_e32 v135, v119, v119
	v_mul_f32_e32 v137, v16, v16
	s_waitcnt lgkmcnt(1)
	v_mov_b32_e32 v147, v144
	s_nop 1
	v_permlane16_swap_b32_e32 v144, v147
	v_add_f32_e32 v144, v144, v147
	v_fmamk_f32 v144, v144, 0x3b800000, v244
	v_mul_f32_e32 v147, 0x4f800000, v144
	v_cmp_gt_f32_e64 s[0:1], s25, v144
	v_fma_f32 v143, -v146, v150, 1.0
	v_fmac_f32_e32 v150, v143, v150
	v_cndmask_b32_e64 v144, v144, v147, s[0:1]
	v_div_scale_f32 v143, vcc, s26, v145, s26
	v_sqrt_f32_e32 v147, v144
	v_mul_f32_e32 v148, v143, v150
	v_fma_f32 v149, -v146, v148, v143
	v_fmac_f32_e32 v148, v149, v150
	v_fma_f32 v143, -v146, v148, v143
	v_add_u32_e32 v146, -1, v147
	s_waitcnt lgkmcnt(0)
	s_nop 1
	v_add_f32_dpp v135, v135, v135 quad_perm:[1,0,3,2] row_mask:0xf bank_mask:0xf
	v_fma_f32 v149, -v146, v147, v144
	v_cmp_ge_f32_e64 s[2:3], 0, v149
	v_add_u32_e32 v149, 1, v147
	v_fmac_f32_e32 v137, v0, v0
	v_cndmask_b32_e64 v146, v147, v146, s[2:3]
	v_fma_f32 v147, -v149, v147, v144
	v_cmp_lt_f32_e64 s[2:3], 0, v147
	s_waitcnt lgkmcnt(0)
	s_nop 1
	v_add_f32_dpp v135, v135, v135 quad_perm:[2,3,0,1] row_mask:0xf bank_mask:0xf
	v_fmac_f32_e32 v137, v38, v38
	v_cndmask_b32_e64 v146, v146, v149, s[2:3]
	v_mul_f32_e32 v147, 0x37800000, v146
	v_cndmask_b32_e64 v146, v146, v147, s[0:1]
	v_cmp_class_f32_e64 s[0:1], v144, v245
	v_fmac_f32_e32 v137, v48, v48
	v_fmac_f32_e32 v137, v70, v70
	v_cndmask_b32_e64 v144, v146, v144, s[0:1]
	s_waitcnt lgkmcnt(0)
	s_nop 1
	v_add_f32_dpp v147, v135, v135 row_half_mirror row_mask:0xf bank_mask:0xf
	v_div_fmas_f32 v135, v143, v150, v148
	v_div_fixup_f32 v135, v135, v145, s26
	v_div_scale_f32 v146, s[0:1], v144, v144, s26
	s_waitcnt lgkmcnt(0)
	s_nop 1
	v_add_f32_dpp v145, v147, v147 row_mirror row_mask:0xf bank_mask:0xf
	v_rcp_f32_e32 v149, v146
	v_fmac_f32_e32 v137, v80, v80
	v_fmac_f32_e32 v137, v102, v102
	v_sub_f32_e32 v118, v118, v156
	s_waitcnt lgkmcnt(0)
	v_mov_b32_e32 v147, v145
	s_nop 1
	v_permlane16_swap_b32_e32 v145, v147
	v_add_f32_e32 v145, v145, v147
	v_fmamk_f32 v145, v145, 0x3b800000, v244
	v_fmac_f32_e32 v137, v118, v118
	v_mul_f32_e32 v147, 0x4f800000, v145
	v_cmp_gt_f32_e64 s[0:1], s25, v145
	v_fma_f32 v143, -v146, v149, 1.0
	v_cndmask_b32_e64 v145, v145, v147, s[0:1]
	v_fmac_f32_e32 v149, v143, v149
	v_div_scale_f32 v143, vcc, s26, v144, s26
	v_sqrt_f32_e32 v147, v145
	v_mul_f32_e32 v148, v143, v149
	v_fma_f32 v150, -v146, v148, v143
	v_fmac_f32_e32 v148, v150, v149
	v_fma_f32 v143, -v146, v148, v143
	v_add_u32_e32 v146, -1, v147
	s_waitcnt lgkmcnt(0)
	s_nop 1
	v_add_f32_dpp v137, v137, v137 quad_perm:[1,0,3,2] row_mask:0xf bank_mask:0xf
	v_fma_f32 v150, -v146, v147, v145
	v_cmp_ge_f32_e64 s[2:3], 0, v150
	v_add_u32_e32 v150, 1, v147
	v_mul_f32_e32 v139, v17, v17
	v_cndmask_b32_e64 v146, v147, v146, s[2:3]
	v_fma_f32 v147, -v150, v147, v145
	v_cmp_lt_f32_e64 s[2:3], 0, v147
	s_waitcnt lgkmcnt(0)
	s_nop 1
	v_add_f32_dpp v137, v137, v137 quad_perm:[2,3,0,1] row_mask:0xf bank_mask:0xf
	v_fmac_f32_e32 v139, v3, v3
	v_cndmask_b32_e64 v146, v146, v150, s[2:3]
	v_mul_f32_e32 v147, 0x37800000, v146
	v_cndmask_b32_e64 v146, v146, v147, s[0:1]
	v_cmp_class_f32_e64 s[0:1], v145, v245
	v_fmac_f32_e32 v139, v39, v39
	v_fmac_f32_e32 v139, v49, v49
	v_cndmask_b32_e64 v145, v146, v145, s[0:1]
	s_waitcnt lgkmcnt(0)
	s_nop 1
	v_add_f32_dpp v147, v137, v137 row_half_mirror row_mask:0xf bank_mask:0xf
	v_div_fmas_f32 v137, v143, v149, v148
	v_div_fixup_f32 v137, v137, v144, s26
	v_div_scale_f32 v146, s[0:1], v145, v145, s26
	s_waitcnt lgkmcnt(0)
	s_nop 1
	v_add_f32_dpp v144, v147, v147 row_mirror row_mask:0xf bank_mask:0xf
	v_fmac_f32_e32 v139, v71, v71
	v_rcp_f32_e32 v150, v146
	v_fmac_f32_e32 v139, v81, v81
	v_fmac_f32_e32 v139, v103, v103
	s_waitcnt lgkmcnt(0)
	v_mov_b32_e32 v147, v144
	s_nop 1
	v_permlane16_swap_b32_e32 v144, v147
	v_add_f32_e32 v144, v144, v147
	v_sub_f32_e32 v120, v120, v157
	v_fmamk_f32 v144, v144, 0x3b800000, v244
	v_fmac_f32_e32 v139, v120, v120
	v_mul_f32_e32 v147, 0x4f800000, v144
	v_cmp_gt_f32_e64 s[0:1], s25, v144
	v_fma_f32 v143, -v146, v150, 1.0
	v_cndmask_b32_e64 v144, v144, v147, s[0:1]
	v_fmac_f32_e32 v150, v143, v150
	v_div_scale_f32 v143, vcc, s26, v145, s26
	v_sqrt_f32_e32 v147, v144
	v_mul_f32_e32 v148, v143, v150
	v_fma_f32 v149, -v146, v148, v143
	v_fmac_f32_e32 v148, v149, v150
	v_fma_f32 v143, -v146, v148, v143
	v_add_u32_e32 v146, -1, v147
	s_waitcnt lgkmcnt(0)
	s_nop 1
	v_add_f32_dpp v139, v139, v139 quad_perm:[1,0,3,2] row_mask:0xf bank_mask:0xf
	v_fma_f32 v149, -v146, v147, v144
	v_cmp_ge_f32_e64 s[2:3], 0, v149
	v_add_u32_e32 v149, 1, v147
	v_mul_f32_e32 v141, v31, v31
	v_cndmask_b32_e64 v146, v147, v146, s[2:3]
	v_fma_f32 v147, -v149, v147, v144
	v_cmp_lt_f32_e64 s[2:3], 0, v147
	s_waitcnt lgkmcnt(0)
	s_nop 1
	v_add_f32_dpp v139, v139, v139 quad_perm:[2,3,0,1] row_mask:0xf bank_mask:0xf
	v_fmac_f32_e32 v141, v15, v15
	v_cndmask_b32_e64 v146, v146, v149, s[2:3]
	v_mul_f32_e32 v147, 0x37800000, v146
	v_cndmask_b32_e64 v146, v146, v147, s[0:1]
	v_cmp_class_f32_e64 s[0:1], v144, v245
	v_fmac_f32_e32 v141, v40, v40
	v_fmac_f32_e32 v141, v63, v63
	v_cndmask_b32_e64 v144, v146, v144, s[0:1]
	s_waitcnt lgkmcnt(0)
	s_nop 1
	v_add_f32_dpp v147, v139, v139 row_half_mirror row_mask:0xf bank_mask:0xf
	v_div_fmas_f32 v139, v143, v150, v148
	v_div_fixup_f32 v139, v139, v145, s26
	v_div_scale_f32 v146, s[0:1], v144, v144, s26
	s_waitcnt lgkmcnt(0)
	s_nop 1
	v_add_f32_dpp v145, v147, v147 row_mirror row_mask:0xf bank_mask:0xf
	v_fmac_f32_e32 v141, v72, v72
	v_rcp_f32_e32 v149, v146
	v_fmac_f32_e32 v141, v95, v95
	v_fmac_f32_e32 v141, v104, v104
	s_waitcnt lgkmcnt(0)
	v_mov_b32_e32 v147, v145
	s_nop 1
	v_permlane16_swap_b32_e32 v145, v147
	v_add_f32_e32 v145, v145, v147
	v_fmamk_f32 v145, v145, 0x3b800000, v244
	v_fmac_f32_e32 v141, v121, v121
	v_mul_f32_e32 v147, 0x4f800000, v145
	v_cmp_gt_f32_e64 s[0:1], s25, v145
	v_fma_f32 v143, -v146, v149, 1.0
	v_cndmask_b32_e64 v145, v145, v147, s[0:1]
	v_fmac_f32_e32 v149, v143, v149
	v_div_scale_f32 v143, vcc, s26, v144, s26
	v_sqrt_f32_e32 v147, v145
	v_mul_f32_e32 v148, v143, v149
	v_fma_f32 v150, -v146, v148, v143
	v_fmac_f32_e32 v148, v150, v149
	v_fma_f32 v143, -v146, v148, v143
	v_add_u32_e32 v146, -1, v147
	s_waitcnt lgkmcnt(0)
	s_nop 1
	v_add_f32_dpp v141, v141, v141 quad_perm:[1,0,3,2] row_mask:0xf bank_mask:0xf
	v_fma_f32 v150, -v146, v147, v145
	v_cmp_ge_f32_e64 s[2:3], 0, v150
	v_add_u32_e32 v150, 1, v147
	v_mul_f32_e32 v142, v30, v30
	v_cndmask_b32_e64 v146, v147, v146, s[2:3]
	v_fma_f32 v147, -v150, v147, v145
	v_cmp_lt_f32_e64 s[2:3], 0, v147
	s_waitcnt lgkmcnt(0)
	s_nop 1
	v_add_f32_dpp v141, v141, v141 quad_perm:[2,3,0,1] row_mask:0xf bank_mask:0xf
	v_fmac_f32_e32 v142, v14, v14
	v_cndmask_b32_e64 v146, v146, v150, s[2:3]
	v_mul_f32_e32 v147, 0x37800000, v146
	v_cndmask_b32_e64 v146, v146, v147, s[0:1]
	v_cmp_class_f32_e64 s[0:1], v145, v245
	v_fmac_f32_e32 v142, v41, v41
	v_fmac_f32_e32 v142, v62, v62
	v_cndmask_b32_e64 v145, v146, v145, s[0:1]
	s_waitcnt lgkmcnt(0)
	s_nop 1
	v_add_f32_dpp v147, v141, v141 row_half_mirror row_mask:0xf bank_mask:0xf
	v_div_fmas_f32 v141, v143, v149, v148
	v_div_fixup_f32 v141, v141, v144, s26
	v_div_scale_f32 v146, s[0:1], v145, v145, s26
	s_waitcnt lgkmcnt(0)
	s_nop 1
	v_add_f32_dpp v144, v147, v147 row_mirror row_mask:0xf bank_mask:0xf
	v_fmac_f32_e32 v142, v73, v73
	v_rcp_f32_e32 v150, v146
	v_fmac_f32_e32 v142, v94, v94
	v_fmac_f32_e32 v142, v105, v105
	s_waitcnt lgkmcnt(0)
	v_mov_b32_e32 v147, v144
	s_nop 1
	v_permlane16_swap_b32_e32 v144, v147
	v_add_f32_e32 v144, v144, v147
	v_fmamk_f32 v144, v144, 0x3b800000, v244
	v_fmac_f32_e32 v142, v124, v124
	v_mul_f32_e32 v147, 0x4f800000, v144
	v_cmp_gt_f32_e64 s[0:1], s25, v144
	v_fma_f32 v143, -v146, v150, 1.0
	v_cndmask_b32_e64 v144, v144, v147, s[0:1]
	v_fmac_f32_e32 v150, v143, v150
	v_div_scale_f32 v143, vcc, s26, v145, s26
	v_sqrt_f32_e32 v147, v144
	v_mul_f32_e32 v148, v143, v150
	v_fma_f32 v149, -v146, v148, v143
	v_fmac_f32_e32 v148, v149, v150
	v_fma_f32 v143, -v146, v148, v143
	v_add_u32_e32 v146, -1, v147
	s_waitcnt lgkmcnt(0)
	s_nop 1
	v_add_f32_dpp v142, v142, v142 quad_perm:[1,0,3,2] row_mask:0xf bank_mask:0xf
	v_fma_f32 v149, -v146, v147, v144
	v_cmp_ge_f32_e64 s[2:3], 0, v149
	v_add_u32_e32 v149, 1, v147
	v_mul_f32_e32 v140, v29, v29
	v_cndmask_b32_e64 v146, v147, v146, s[2:3]
	v_fma_f32 v147, -v149, v147, v144
	v_cmp_lt_f32_e64 s[2:3], 0, v147
	s_waitcnt lgkmcnt(0)
	s_nop 1
	v_add_f32_dpp v142, v142, v142 quad_perm:[2,3,0,1] row_mask:0xf bank_mask:0xf
	v_fmac_f32_e32 v140, v13, v13
	v_cndmask_b32_e64 v146, v146, v149, s[2:3]
	v_mul_f32_e32 v147, 0x37800000, v146
	v_cndmask_b32_e64 v146, v146, v147, s[0:1]
	v_cmp_class_f32_e64 s[0:1], v144, v245
	v_fmac_f32_e32 v140, v42, v42
	v_fmac_f32_e32 v140, v61, v61
	v_cndmask_b32_e64 v144, v146, v144, s[0:1]
	s_waitcnt lgkmcnt(0)
	s_nop 1
	v_add_f32_dpp v147, v142, v142 row_half_mirror row_mask:0xf bank_mask:0xf
	v_div_fmas_f32 v142, v143, v150, v148
	v_div_fixup_f32 v142, v142, v145, s26
	v_div_scale_f32 v146, s[0:1], v144, v144, s26
	s_waitcnt lgkmcnt(0)
	s_nop 1
	v_add_f32_dpp v145, v147, v147 row_mirror row_mask:0xf bank_mask:0xf
	v_fmac_f32_e32 v140, v74, v74
	v_rcp_f32_e32 v149, v146
	v_fmac_f32_e32 v140, v93, v93
	v_fmac_f32_e32 v140, v106, v106
	s_waitcnt lgkmcnt(0)
	v_mov_b32_e32 v147, v145
	s_nop 1
	v_permlane16_swap_b32_e32 v145, v147
	v_add_f32_e32 v145, v145, v147
	v_fmamk_f32 v145, v145, 0x3b800000, v244
	v_fmac_f32_e32 v140, v122, v122
	v_mul_f32_e32 v147, 0x4f800000, v145
	v_cmp_gt_f32_e64 s[0:1], s25, v145
	v_fma_f32 v143, -v146, v149, 1.0
	v_cndmask_b32_e64 v145, v145, v147, s[0:1]
	v_fmac_f32_e32 v149, v143, v149
	v_div_scale_f32 v143, vcc, s26, v144, s26
	v_sqrt_f32_e32 v147, v145
	v_mul_f32_e32 v148, v143, v149
	v_fma_f32 v150, -v146, v148, v143
	v_fmac_f32_e32 v148, v150, v149
	v_fma_f32 v143, -v146, v148, v143
	v_add_u32_e32 v146, -1, v147
	s_waitcnt lgkmcnt(0)
	s_nop 1
	v_add_f32_dpp v140, v140, v140 quad_perm:[1,0,3,2] row_mask:0xf bank_mask:0xf
	v_fma_f32 v150, -v146, v147, v145
	v_cmp_ge_f32_e64 s[2:3], 0, v150
	v_add_u32_e32 v150, 1, v147
	v_mul_f32_e32 v138, v28, v28
	v_cndmask_b32_e64 v146, v147, v146, s[2:3]
	v_fma_f32 v147, -v150, v147, v145
	v_cmp_lt_f32_e64 s[2:3], 0, v147
	s_waitcnt lgkmcnt(0)
	s_nop 1
	v_add_f32_dpp v140, v140, v140 quad_perm:[2,3,0,1] row_mask:0xf bank_mask:0xf
	v_fmac_f32_e32 v138, v12, v12
	v_cndmask_b32_e64 v146, v146, v150, s[2:3]
	v_mul_f32_e32 v147, 0x37800000, v146
	v_cndmask_b32_e64 v146, v146, v147, s[0:1]
	v_cmp_class_f32_e64 s[0:1], v145, v245
	v_fmac_f32_e32 v138, v43, v43
	v_fmac_f32_e32 v138, v60, v60
	v_cndmask_b32_e64 v145, v146, v145, s[0:1]
	s_waitcnt lgkmcnt(0)
	s_nop 1
	v_add_f32_dpp v147, v140, v140 row_half_mirror row_mask:0xf bank_mask:0xf
	v_div_fmas_f32 v140, v143, v149, v148
	v_div_fixup_f32 v140, v140, v144, s26
	v_div_scale_f32 v146, s[0:1], v145, v145, s26
	s_waitcnt lgkmcnt(0)
	s_nop 1
	v_add_f32_dpp v144, v147, v147 row_mirror row_mask:0xf bank_mask:0xf
	v_fmac_f32_e32 v138, v75, v75
	v_rcp_f32_e32 v150, v146
	v_fmac_f32_e32 v138, v92, v92
	v_fmac_f32_e32 v138, v107, v107
	s_waitcnt lgkmcnt(0)
	v_mov_b32_e32 v147, v144
	s_nop 1
	v_permlane16_swap_b32_e32 v144, v147
	v_add_f32_e32 v144, v144, v147
	v_fmamk_f32 v144, v144, 0x3b800000, v244
	v_fmac_f32_e32 v138, v125, v125
	v_mul_f32_e32 v147, 0x4f800000, v144
	v_cmp_gt_f32_e64 s[0:1], s25, v144
	v_fma_f32 v143, -v146, v150, 1.0
	v_cndmask_b32_e64 v144, v144, v147, s[0:1]
	v_fmac_f32_e32 v150, v143, v150
	v_div_scale_f32 v143, vcc, s26, v145, s26
	v_sqrt_f32_e32 v147, v144
	v_mul_f32_e32 v148, v143, v150
	v_fma_f32 v149, -v146, v148, v143
	v_fmac_f32_e32 v148, v149, v150
	v_fma_f32 v143, -v146, v148, v143
	v_add_u32_e32 v146, -1, v147
	s_waitcnt lgkmcnt(0)
	s_nop 1
	v_add_f32_dpp v138, v138, v138 quad_perm:[1,0,3,2] row_mask:0xf bank_mask:0xf
	v_fma_f32 v149, -v146, v147, v144
	v_cmp_ge_f32_e64 s[2:3], 0, v149
	v_add_u32_e32 v149, 1, v147
	v_mul_f32_e32 v136, v27, v27
	v_cndmask_b32_e64 v146, v147, v146, s[2:3]
	v_fma_f32 v147, -v149, v147, v144
	v_cmp_lt_f32_e64 s[2:3], 0, v147
	s_waitcnt lgkmcnt(0)
	s_nop 1
	v_add_f32_dpp v138, v138, v138 quad_perm:[2,3,0,1] row_mask:0xf bank_mask:0xf
	v_fmac_f32_e32 v136, v11, v11
	v_cndmask_b32_e64 v146, v146, v149, s[2:3]
	v_mul_f32_e32 v147, 0x37800000, v146
	v_cndmask_b32_e64 v146, v146, v147, s[0:1]
	v_cmp_class_f32_e64 s[0:1], v144, v245
	v_fmac_f32_e32 v136, v44, v44
	v_fmac_f32_e32 v136, v59, v59
	v_cndmask_b32_e64 v144, v146, v144, s[0:1]
	s_waitcnt lgkmcnt(0)
	s_nop 1
	v_add_f32_dpp v147, v138, v138 row_half_mirror row_mask:0xf bank_mask:0xf
	v_div_fmas_f32 v138, v143, v150, v148
	v_div_fixup_f32 v138, v138, v145, s26
	v_div_scale_f32 v146, s[0:1], v144, v144, s26
	s_waitcnt lgkmcnt(0)
	s_nop 1
	v_add_f32_dpp v145, v147, v147 row_mirror row_mask:0xf bank_mask:0xf
	v_fmac_f32_e32 v136, v76, v76
	v_rcp_f32_e32 v149, v146
	v_fmac_f32_e32 v136, v91, v91
	v_fmac_f32_e32 v136, v108, v108
	s_waitcnt lgkmcnt(0)
	v_mov_b32_e32 v147, v145
	s_nop 1
	v_permlane16_swap_b32_e32 v145, v147
	v_add_f32_e32 v145, v145, v147
	v_fmamk_f32 v145, v145, 0x3b800000, v244
	v_fmac_f32_e32 v136, v123, v123
	v_mul_f32_e32 v147, 0x4f800000, v145
	v_cmp_gt_f32_e64 s[0:1], s25, v145
	v_fma_f32 v143, -v146, v149, 1.0
	v_cndmask_b32_e64 v145, v145, v147, s[0:1]
	v_fmac_f32_e32 v149, v143, v149
	v_div_scale_f32 v143, vcc, s26, v144, s26
	v_sqrt_f32_e32 v147, v145
	v_mul_f32_e32 v148, v143, v149
	v_fma_f32 v150, -v146, v148, v143
	v_fmac_f32_e32 v148, v150, v149
	v_fma_f32 v143, -v146, v148, v143
	v_add_u32_e32 v146, -1, v147
	s_waitcnt lgkmcnt(0)
	s_nop 1
	v_add_f32_dpp v136, v136, v136 quad_perm:[1,0,3,2] row_mask:0xf bank_mask:0xf
	v_fma_f32 v150, -v146, v147, v145
	v_cmp_ge_f32_e64 s[2:3], 0, v150
	v_add_u32_e32 v150, 1, v147
	v_mul_f32_e32 v134, v26, v26
	v_cndmask_b32_e64 v146, v147, v146, s[2:3]
	v_fma_f32 v147, -v150, v147, v145
	v_cmp_lt_f32_e64 s[2:3], 0, v147
	s_waitcnt lgkmcnt(0)
	s_nop 1
	v_add_f32_dpp v136, v136, v136 quad_perm:[2,3,0,1] row_mask:0xf bank_mask:0xf
	v_fmac_f32_e32 v134, v8, v8
	v_cndmask_b32_e64 v146, v146, v150, s[2:3]
	v_mul_f32_e32 v147, 0x37800000, v146
	v_cndmask_b32_e64 v146, v146, v147, s[0:1]
	v_cmp_class_f32_e64 s[0:1], v145, v245
	v_fmac_f32_e32 v134, v45, v45
	v_fmac_f32_e32 v134, v58, v58
	v_cndmask_b32_e64 v145, v146, v145, s[0:1]
	s_waitcnt lgkmcnt(0)
	s_nop 1
	v_add_f32_dpp v147, v136, v136 row_half_mirror row_mask:0xf bank_mask:0xf
	v_div_fmas_f32 v136, v143, v149, v148
	v_div_fixup_f32 v136, v136, v144, s26
	v_div_scale_f32 v146, s[0:1], v145, v145, s26
	s_waitcnt lgkmcnt(0)
	s_nop 1
	v_add_f32_dpp v144, v147, v147 row_mirror row_mask:0xf bank_mask:0xf
	v_fmac_f32_e32 v134, v77, v77
	v_rcp_f32_e32 v150, v146
	v_fmac_f32_e32 v134, v90, v90
	v_fmac_f32_e32 v134, v109, v109
	s_waitcnt lgkmcnt(0)
	v_mov_b32_e32 v147, v144
	s_nop 1
	v_permlane16_swap_b32_e32 v144, v147
	v_add_f32_e32 v144, v144, v147
	v_sub_f32_e32 v127, v127, v153
	v_fmamk_f32 v144, v144, 0x3b800000, v244
	v_fmac_f32_e32 v134, v127, v127
	v_mul_f32_e32 v147, 0x4f800000, v144
	v_cmp_gt_f32_e64 s[0:1], s25, v144
	v_fma_f32 v143, -v146, v150, 1.0
	v_cndmask_b32_e64 v144, v144, v147, s[0:1]
	v_fmac_f32_e32 v150, v143, v150
	v_div_scale_f32 v143, vcc, s26, v145, s26
	v_sqrt_f32_e32 v147, v144
	v_mul_f32_e32 v148, v143, v150
	v_fma_f32 v149, -v146, v148, v143
	v_fmac_f32_e32 v148, v149, v150
	v_fma_f32 v143, -v146, v148, v143
	v_add_u32_e32 v146, -1, v147
	s_waitcnt lgkmcnt(0)
	s_nop 1
	v_add_f32_dpp v134, v134, v134 quad_perm:[1,0,3,2] row_mask:0xf bank_mask:0xf
	v_fma_f32 v149, -v146, v147, v144
	v_cmp_ge_f32_e64 s[2:3], 0, v149
	v_add_u32_e32 v149, 1, v147
	v_mul_f32_e32 v132, v24, v24
	v_cndmask_b32_e64 v146, v147, v146, s[2:3]
	v_fma_f32 v147, -v149, v147, v144
	v_cmp_lt_f32_e64 s[2:3], 0, v147
	s_waitcnt lgkmcnt(0)
	s_nop 1
	v_add_f32_dpp v134, v134, v134 quad_perm:[2,3,0,1] row_mask:0xf bank_mask:0xf
	v_fmac_f32_e32 v132, v6, v6
	v_cndmask_b32_e64 v146, v146, v149, s[2:3]
	v_mul_f32_e32 v147, 0x37800000, v146
	v_cndmask_b32_e64 v146, v146, v147, s[0:1]
	v_cmp_class_f32_e64 s[0:1], v144, v245
	v_fmac_f32_e32 v132, v46, v46
	v_fmac_f32_e32 v132, v56, v56
	v_cndmask_b32_e64 v144, v146, v144, s[0:1]
	s_waitcnt lgkmcnt(0)
	s_nop 1
	v_add_f32_dpp v147, v134, v134 row_half_mirror row_mask:0xf bank_mask:0xf
	v_div_fmas_f32 v134, v143, v150, v148
	v_div_fixup_f32 v134, v134, v145, s26
	v_div_scale_f32 v146, s[0:1], v144, v144, s26
	s_waitcnt lgkmcnt(0)
	s_nop 1
	v_add_f32_dpp v145, v147, v147 row_mirror row_mask:0xf bank_mask:0xf
	v_fmac_f32_e32 v132, v78, v78
	v_rcp_f32_e32 v149, v146
	v_fmac_f32_e32 v132, v88, v88
	v_fmac_f32_e32 v132, v110, v110
	s_waitcnt lgkmcnt(0)
	v_mov_b32_e32 v147, v145
	s_nop 1
	v_permlane16_swap_b32_e32 v145, v147
	v_add_f32_e32 v145, v145, v147
	v_sub_f32_e32 v126, v126, v154
	v_fmamk_f32 v145, v145, 0x3b800000, v244
	v_fmac_f32_e32 v132, v126, v126
	v_mul_f32_e32 v147, 0x4f800000, v145
	v_cmp_gt_f32_e64 s[0:1], s25, v145
	v_fma_f32 v143, -v146, v149, 1.0
	v_cndmask_b32_e64 v145, v145, v147, s[0:1]
	v_fmac_f32_e32 v149, v143, v149
	v_div_scale_f32 v143, vcc, s26, v144, s26
	v_sqrt_f32_e32 v147, v145
	v_mul_f32_e32 v148, v143, v149
	v_fma_f32 v150, -v146, v148, v143
	v_fmac_f32_e32 v148, v150, v149
	v_fma_f32 v143, -v146, v148, v143
	v_add_u32_e32 v146, -1, v147
	s_waitcnt lgkmcnt(0)
	s_nop 1
	v_add_f32_dpp v132, v132, v132 quad_perm:[1,0,3,2] row_mask:0xf bank_mask:0xf
	v_fma_f32 v150, -v146, v147, v145
	v_cmp_ge_f32_e64 s[2:3], 0, v150
	v_add_u32_e32 v150, 1, v147
	v_mul_f32_e32 v130, v25, v25
	v_cndmask_b32_e64 v146, v147, v146, s[2:3]
	v_fma_f32 v147, -v150, v147, v145
	v_cmp_lt_f32_e64 s[2:3], 0, v147
	s_waitcnt lgkmcnt(0)
	s_nop 1
	v_add_f32_dpp v132, v132, v132 quad_perm:[2,3,0,1] row_mask:0xf bank_mask:0xf
	v_fmac_f32_e32 v130, v9, v9
	v_cndmask_b32_e64 v146, v146, v150, s[2:3]
	v_mul_f32_e32 v147, 0x37800000, v146
	v_cndmask_b32_e64 v146, v146, v147, s[0:1]
	v_cmp_class_f32_e64 s[0:1], v145, v245
	v_fmac_f32_e32 v130, v47, v47
	v_fmac_f32_e32 v130, v57, v57
	v_cndmask_b32_e64 v145, v146, v145, s[0:1]
	v_div_scale_f32 v146, s[0:1], v145, v145, s26
	s_waitcnt lgkmcnt(0)
	s_nop 1
	v_add_f32_dpp v147, v132, v132 row_half_mirror row_mask:0xf bank_mask:0xf
	v_rcp_f32_e32 v150, v146
	v_div_fmas_f32 v132, v143, v149, v148
	v_div_fixup_f32 v132, v132, v144, s26
	v_fma_f32 v143, -v146, v150, 1.0
	v_fmac_f32_e32 v150, v143, v150
	s_waitcnt lgkmcnt(0)
	s_nop 1
	v_add_f32_dpp v143, v147, v147 row_mirror row_mask:0xf bank_mask:0xf
	v_fmac_f32_e32 v130, v79, v79
	v_fmac_f32_e32 v130, v89, v89
	v_fmac_f32_e32 v130, v111, v111
	v_sub_f32_e32 v128, v128, v155
	s_waitcnt lgkmcnt(0)
	v_mov_b32_e32 v144, v143
	s_nop 1
	v_permlane16_swap_b32_e32 v143, v144
	v_add_f32_e32 v143, v143, v144
	v_fmamk_f32 v143, v143, 0x3b800000, v244
	v_fmac_f32_e32 v130, v128, v128
	v_mul_f32_e32 v144, 0x4f800000, v143
	v_cmp_gt_f32_e64 s[0:1], s25, v143
	v_div_scale_f32 v147, vcc, s26, v145, s26
	v_cndmask_b32_e64 v143, v143, v144, s[0:1]
	v_sqrt_f32_e32 v144, v143
	v_mul_f32_e32 v148, v147, v150
	v_fma_f32 v149, -v146, v148, v147
	v_fmac_f32_e32 v148, v149, v150
	v_fma_f32 v146, -v146, v148, v147
	v_add_u32_e32 v147, -1, v144
	s_waitcnt lgkmcnt(0)
	s_nop 1
	v_add_f32_dpp v130, v130, v130 quad_perm:[1,0,3,2] row_mask:0xf bank_mask:0xf
	v_fma_f32 v151, -v147, v144, v143
	v_cmp_ge_f32_e64 s[2:3], 0, v151
	v_add_u32_e32 v151, 1, v144
	global_load_dword v149, v[196:197], off
	v_cndmask_b32_e64 v147, v144, v147, s[2:3]
	v_fma_f32 v144, -v151, v144, v143
	v_cmp_lt_f32_e64 s[2:3], 0, v144
	s_waitcnt lgkmcnt(0)
	s_nop 1
	v_add_f32_dpp v130, v130, v130 quad_perm:[2,3,0,1] row_mask:0xf bank_mask:0xf
	v_mul_f32_e32 v112, v112, v129
	v_cndmask_b32_e64 v144, v147, v151, s[2:3]
	v_mul_f32_e32 v147, 0x37800000, v144
	v_cndmask_b32_e64 v144, v144, v147, s[0:1]
	v_cmp_class_f32_e64 s[0:1], v143, v245
	v_lshlrev_b32_e32 v153, 12, v222
	v_mul_f32_e32 v22, v22, v129
	v_cndmask_b32_e64 v143, v144, v143, s[0:1]
	v_div_scale_f32 v144, s[0:1], v143, v143, s26
	s_waitcnt lgkmcnt(0)
	s_nop 1
	v_add_f32_dpp v147, v130, v130 row_half_mirror row_mask:0xf bank_mask:0xf
	v_rcp_f32_e32 v151, v144
	v_div_fmas_f32 v130, v146, v150, v148
	v_div_fixup_f32 v130, v130, v145, s26
	v_fma_f32 v145, -v144, v151, 1.0
	global_load_dword v148, v[196:197], off offset:128
	v_fmac_f32_e32 v151, v145, v151
	s_waitcnt lgkmcnt(0)
	s_nop 1
	v_add_f32_dpp v145, v147, v147 row_mirror row_mask:0xf bank_mask:0xf
	v_div_scale_f32 v147, vcc, s26, v143, s26
	v_mul_f32_e32 v150, v147, v151
	v_fma_f32 v152, -v144, v150, v147
	s_waitcnt lgkmcnt(0)
	v_mov_b32_e32 v146, v145
	s_nop 1
	v_permlane16_swap_b32_e32 v145, v146
	v_add_f32_e32 v145, v145, v146
	v_fmamk_f32 v145, v145, 0x3b800000, v244
	v_mul_f32_e32 v146, 0x4f800000, v145
	v_cmp_gt_f32_e64 s[0:1], s25, v145
	v_fmac_f32_e32 v150, v152, v151
	v_fma_f32 v144, -v144, v150, v147
	v_cndmask_b32_e64 v145, v145, v146, s[0:1]
	v_sqrt_f32_e32 v146, v145
	v_div_fmas_f32 v144, v144, v151, v150
	v_div_fixup_f32 v143, v144, v143, s26
	v_add3_u32 v153, s39, v194, v153
	v_add_u32_e32 v147, -1, v146
	v_fma_f32 v152, -v147, v146, v145
	v_cmp_ge_f32_e64 s[2:3], 0, v152
	v_add_u32_e32 v152, 1, v146
	v_mul_f32_e32 v10, v10, v131
	v_cndmask_b32_e64 v147, v146, v147, s[2:3]
	v_fma_f32 v146, -v152, v146, v145
	v_cmp_lt_f32_e64 s[2:3], 0, v146
	v_mul_f32_e32 v7, v7, v133
	v_mul_f32_e32 v5, v5, v135
	v_cndmask_b32_e64 v146, v147, v152, s[2:3]
	v_mul_f32_e32 v147, 0x37800000, v146
	v_cndmask_b32_e64 v146, v146, v147, s[0:1]
	v_cmp_class_f32_e64 s[0:1], v145, v245
	v_mul_f32_e32 v4, v4, v137
	v_mul_f32_e32 v2, v2, v139
	v_cndmask_b32_e64 v145, v146, v145, s[0:1]
	v_div_scale_f32 v146, s[0:1], v145, v145, s26
	v_rcp_f32_e32 v147, v146
	v_mul_f32_e32 v0, v0, v141
	v_mul_f32_e32 v3, v3, v142
	v_mul_f32_e32 v15, v15, v140
	v_fma_f32 v144, -v146, v147, 1.0
	v_fmac_f32_e32 v147, v144, v147
	v_div_scale_f32 v144, vcc, s26, v145, s26
	v_mul_f32_e32 v150, v144, v147
	v_fma_f32 v151, -v146, v150, v144
	v_fmac_f32_e32 v150, v151, v147
	v_fma_f32 v144, -v146, v150, v144
	v_div_fmas_f32 v144, v144, v147, v150
	v_div_fixup_f32 v144, v144, v145, s26
	global_load_dword v145, v[196:197], off offset:256
	global_load_dword v146, v[196:197], off offset:384
	global_load_dword v147, v[196:197], off offset:512
	global_load_dword v150, v[196:197], off offset:640
	global_load_dword v151, v[196:197], off offset:768
	global_load_dword v152, v[196:197], off offset:896
	v_mul_f32_e32 v14, v14, v138
	v_mul_f32_e32 v13, v13, v136
	v_mul_f32_e32 v12, v12, v134
	v_mul_f32_e32 v11, v11, v132
	v_mul_f32_e32 v8, v8, v130
	s_waitcnt vmcnt(7)
	v_mul_f32_e32 v112, v112, v149
	v_mul_f32_e32 v10, v10, v149
	v_mul_f32_e32 v7, v7, v149
	v_mul_f32_e32 v5, v5, v149
	v_mul_f32_e32 v4, v4, v149
	v_mul_f32_e32 v2, v2, v149
	v_mul_f32_e32 v0, v0, v149
	v_mul_f32_e32 v3, v3, v149
	v_mul_f32_e32 v15, v15, v149
	v_mul_f32_e32 v14, v14, v149
	v_mul_f32_e32 v13, v13, v149
	v_mul_f32_e32 v12, v12, v149
	v_mul_f32_e32 v11, v11, v149
	v_mul_f32_e32 v8, v8, v149
	v_mul_f32_e32 v6, v6, v143
	v_mul_f32_e32 v6, v149, v6
	v_mul_f32_e32 v9, v9, v144
	v_mul_f32_e32 v9, v149, v9
	s_add_i32 s0, s4, s33
	s_add_i32 s4, s0, s37
	s_lshl_b32 s0, s36, 5
	s_and_b32 s0, s0, 0xe00
	s_waitcnt vmcnt(6)
	v_mul_f32_e32 v22, v22, v148
	ds_write2_b32 v153, v112, v22 offset1:32
	v_mul_f32_e32 v22, v23, v131
	v_mul_f32_e32 v22, v22, v148
	v_add_u32_e32 v23, 0x400, v153
	ds_write2_b32 v23, v10, v22 offset1:32
	v_mul_f32_e32 v10, v21, v133
	v_mul_f32_e32 v10, v10, v148
	v_add_u32_e32 v21, 0x800, v153
	ds_write2_b32 v21, v7, v10 offset1:32
	v_mul_f32_e32 v7, v20, v135
	v_mul_f32_e32 v7, v7, v148
	v_add_u32_e32 v10, 0xc00, v153
	ds_write2_b32 v10, v5, v7 offset1:32
	v_mul_f32_e32 v5, v19, v137
	v_mul_f32_e32 v5, v5, v148
	v_add_u32_e32 v7, 0x2000, v153
	ds_write2_b32 v7, v4, v5 offset1:32
	v_mul_f32_e32 v4, v18, v139
	v_mul_f32_e32 v4, v4, v148
	v_add_u32_e32 v5, 0x2400, v153
	ds_write2_b32 v5, v2, v4 offset1:32
	v_mul_f32_e32 v2, v16, v141
	v_mul_f32_e32 v2, v2, v148
	v_add_u32_e32 v4, 0x2800, v153
	ds_write2_b32 v4, v0, v2 offset1:32
	v_mul_f32_e32 v0, v17, v142
	v_mul_f32_e32 v0, v0, v148
	v_add_u32_e32 v2, 0x2c00, v153
	ds_write2_b32 v2, v3, v0 offset1:32
	v_mul_f32_e32 v0, v31, v140
	v_mul_f32_e32 v0, v0, v148
	v_add_u32_e32 v3, 0x4000, v153
	ds_write2_b32 v3, v15, v0 offset1:32
	v_mul_f32_e32 v0, v30, v138
	v_mul_f32_e32 v0, v0, v148
	v_add_u32_e32 v15, 0x4400, v153
	ds_write2_b32 v15, v14, v0 offset1:32
	v_mul_f32_e32 v0, v29, v136
	v_mul_f32_e32 v0, v0, v148
	v_add_u32_e32 v14, 0x4800, v153
	ds_write2_b32 v14, v13, v0 offset1:32
	v_mul_f32_e32 v0, v28, v134
	v_mul_f32_e32 v0, v0, v148
	v_add_u32_e32 v13, 0x4c00, v153
	ds_write2_b32 v13, v12, v0 offset1:32
	v_mul_f32_e32 v0, v27, v132
	v_mul_f32_e32 v0, v0, v148
	v_add_u32_e32 v12, 0x6000, v153
	ds_write2_b32 v12, v11, v0 offset1:32
	v_mul_f32_e32 v0, v26, v130
	v_mul_f32_e32 v0, v0, v148
	v_add_u32_e32 v11, 0x6400, v153
	ds_write2_b32 v11, v8, v0 offset1:32
	v_mul_f32_e32 v0, v24, v143
	v_mul_f32_e32 v0, v0, v148
	v_add_u32_e32 v8, 0x6800, v153
	ds_write2_b32 v8, v6, v0 offset1:32
	v_mul_f32_e32 v0, v25, v144
	v_mul_f32_e32 v0, v0, v148
	v_add_u32_e32 v6, 0x6c00, v153
	ds_write2_b32 v6, v9, v0 offset1:32
	v_mul_f32_e32 v0, v32, v129
	v_mul_f32_e32 v32, v55, v129
	s_waitcnt vmcnt(5)
	v_mul_f32_e32 v0, v0, v145
	s_waitcnt vmcnt(4)
	v_mul_f32_e32 v32, v32, v146
	v_mul_f32_e32 v9, v33, v131
	ds_write2_b32 v153, v0, v32 offset0:64 offset1:96
	v_mul_f32_e32 v0, v54, v131
	v_mul_f32_e32 v9, v9, v145
	v_mul_f32_e32 v0, v0, v146
	v_mul_f32_e32 v16, v34, v133
	ds_write2_b32 v23, v9, v0 offset0:64 offset1:96
	v_mul_f32_e32 v0, v53, v133
	v_mul_f32_e32 v16, v16, v145
	v_mul_f32_e32 v0, v0, v146
	v_mul_f32_e32 v17, v35, v135
	ds_write2_b32 v21, v16, v0 offset0:64 offset1:96
	v_mul_f32_e32 v0, v52, v135
	v_mul_f32_e32 v17, v17, v145
	v_mul_f32_e32 v0, v0, v146
	v_mul_f32_e32 v18, v36, v137
	ds_write2_b32 v10, v17, v0 offset0:64 offset1:96
	v_mul_f32_e32 v0, v51, v137
	v_mul_f32_e32 v18, v18, v145
	v_mul_f32_e32 v0, v0, v146
	v_mul_f32_e32 v19, v37, v139
	ds_write2_b32 v7, v18, v0 offset0:64 offset1:96
	v_mul_f32_e32 v0, v50, v139
	v_mul_f32_e32 v19, v19, v145
	v_mul_f32_e32 v0, v0, v146
	v_mul_f32_e32 v20, v38, v141
	ds_write2_b32 v5, v19, v0 offset0:64 offset1:96
	v_mul_f32_e32 v0, v48, v141
	v_mul_f32_e32 v20, v20, v145
	v_mul_f32_e32 v0, v0, v146
	v_mul_f32_e32 v22, v39, v142
	ds_write2_b32 v4, v20, v0 offset0:64 offset1:96
	v_mul_f32_e32 v0, v49, v142
	v_mul_f32_e32 v22, v22, v145
	v_mul_f32_e32 v0, v0, v146
	v_mul_f32_e32 v24, v40, v140
	ds_write2_b32 v2, v22, v0 offset0:64 offset1:96
	v_mul_f32_e32 v0, v63, v140
	v_mul_f32_e32 v24, v24, v145
	v_mul_f32_e32 v0, v0, v146
	v_mul_f32_e32 v25, v41, v138
	ds_write2_b32 v3, v24, v0 offset0:64 offset1:96
	v_mul_f32_e32 v0, v62, v138
	v_mul_f32_e32 v25, v25, v145
	v_mul_f32_e32 v0, v0, v146
	v_mul_f32_e32 v26, v42, v136
	ds_write2_b32 v15, v25, v0 offset0:64 offset1:96
	v_mul_f32_e32 v0, v61, v136
	v_mul_f32_e32 v26, v26, v145
	v_mul_f32_e32 v0, v0, v146
	v_mul_f32_e32 v27, v43, v134
	ds_write2_b32 v14, v26, v0 offset0:64 offset1:96
	v_mul_f32_e32 v0, v60, v134
	v_mul_f32_e32 v27, v27, v145
	v_mul_f32_e32 v0, v0, v146
	v_mul_f32_e32 v28, v44, v132
	ds_write2_b32 v13, v27, v0 offset0:64 offset1:96
	v_mul_f32_e32 v0, v59, v132
	v_mul_f32_e32 v28, v28, v145
	v_mul_f32_e32 v0, v0, v146
	v_mul_f32_e32 v29, v45, v130
	ds_write2_b32 v12, v28, v0 offset0:64 offset1:96
	v_mul_f32_e32 v0, v58, v130
	v_mul_f32_e32 v29, v29, v145
	v_mul_f32_e32 v0, v0, v146
	v_mul_f32_e32 v30, v46, v143
	ds_write2_b32 v11, v29, v0 offset0:64 offset1:96
	v_mul_f32_e32 v0, v56, v143
	v_mul_f32_e32 v30, v30, v145
	v_mul_f32_e32 v0, v0, v146
	v_mul_f32_e32 v31, v47, v144
	ds_write2_b32 v8, v30, v0 offset0:64 offset1:96
	v_mul_f32_e32 v0, v57, v144
	v_mul_f32_e32 v31, v31, v145
	v_mul_f32_e32 v0, v0, v146
	ds_write2_b32 v6, v31, v0 offset0:64 offset1:96
	v_mul_f32_e32 v0, v64, v129
	v_mul_f32_e32 v32, v87, v129
	s_waitcnt vmcnt(3)
	v_mul_f32_e32 v0, v0, v147
	s_waitcnt vmcnt(2)
	v_mul_f32_e32 v32, v32, v150
	v_mul_f32_e32 v9, v65, v131
	ds_write2_b32 v153, v0, v32 offset0:128 offset1:160
	v_mul_f32_e32 v0, v86, v131
	v_mul_f32_e32 v9, v9, v147
	v_mul_f32_e32 v0, v0, v150
	v_mul_f32_e32 v16, v66, v133
	ds_write2_b32 v23, v9, v0 offset0:128 offset1:160
	v_mul_f32_e32 v0, v85, v133
	v_mul_f32_e32 v16, v16, v147
	v_mul_f32_e32 v0, v0, v150
	v_mul_f32_e32 v17, v67, v135
	ds_write2_b32 v21, v16, v0 offset0:128 offset1:160
	v_mul_f32_e32 v0, v84, v135
	v_mul_f32_e32 v17, v17, v147
	v_mul_f32_e32 v0, v0, v150
	v_mul_f32_e32 v18, v68, v137
	ds_write2_b32 v10, v17, v0 offset0:128 offset1:160
	v_mul_f32_e32 v0, v83, v137
	v_mul_f32_e32 v18, v18, v147
	v_mul_f32_e32 v0, v0, v150
	v_mul_f32_e32 v19, v69, v139
	ds_write2_b32 v7, v18, v0 offset0:128 offset1:160
	v_mul_f32_e32 v0, v82, v139
	v_mul_f32_e32 v19, v19, v147
	v_mul_f32_e32 v0, v0, v150
	v_mul_f32_e32 v20, v70, v141
	ds_write2_b32 v5, v19, v0 offset0:128 offset1:160
	v_mul_f32_e32 v0, v80, v141
	v_mul_f32_e32 v20, v20, v147
	v_mul_f32_e32 v0, v0, v150
	v_mul_f32_e32 v22, v71, v142
	ds_write2_b32 v4, v20, v0 offset0:128 offset1:160
	v_mul_f32_e32 v0, v81, v142
	v_mul_f32_e32 v22, v22, v147
	v_mul_f32_e32 v0, v0, v150
	v_mul_f32_e32 v24, v72, v140
	ds_write2_b32 v2, v22, v0 offset0:128 offset1:160
	v_mul_f32_e32 v0, v95, v140
	v_mul_f32_e32 v24, v24, v147
	v_mul_f32_e32 v0, v0, v150
	v_mul_f32_e32 v25, v73, v138
	ds_write2_b32 v3, v24, v0 offset0:128 offset1:160
	v_mul_f32_e32 v0, v94, v138
	v_mul_f32_e32 v25, v25, v147
	v_mul_f32_e32 v0, v0, v150
	v_mul_f32_e32 v26, v74, v136
	ds_write2_b32 v15, v25, v0 offset0:128 offset1:160
	v_mul_f32_e32 v0, v93, v136
	v_mul_f32_e32 v26, v26, v147
	v_mul_f32_e32 v0, v0, v150
	v_mul_f32_e32 v27, v75, v134
	ds_write2_b32 v14, v26, v0 offset0:128 offset1:160
	v_mul_f32_e32 v0, v92, v134
	v_mul_f32_e32 v27, v27, v147
	v_mul_f32_e32 v0, v0, v150
	v_mul_f32_e32 v28, v76, v132
	ds_write2_b32 v13, v27, v0 offset0:128 offset1:160
	v_mul_f32_e32 v0, v91, v132
	v_mul_f32_e32 v28, v28, v147
	v_mul_f32_e32 v0, v0, v150
	v_mul_f32_e32 v29, v77, v130
	ds_write2_b32 v12, v28, v0 offset0:128 offset1:160
	v_mul_f32_e32 v0, v90, v130
	v_mul_f32_e32 v29, v29, v147
	v_mul_f32_e32 v0, v0, v150
	v_mul_f32_e32 v30, v78, v143
	ds_write2_b32 v11, v29, v0 offset0:128 offset1:160
	v_mul_f32_e32 v0, v88, v143
	v_mul_f32_e32 v30, v30, v147
	v_mul_f32_e32 v0, v0, v150
	v_mul_f32_e32 v31, v79, v144
	ds_write2_b32 v8, v30, v0 offset0:128 offset1:160
	v_mul_f32_e32 v0, v89, v144
	v_mul_f32_e32 v31, v31, v147
	v_mul_f32_e32 v0, v0, v150
	ds_write2_b32 v6, v31, v0 offset0:128 offset1:160
	v_mul_f32_e32 v0, v96, v129
	v_mul_f32_e32 v32, v117, v129
	s_waitcnt vmcnt(1)
	v_mul_f32_e32 v0, v0, v151
	s_waitcnt vmcnt(0)
	v_mul_f32_e32 v32, v32, v152
	v_mul_f32_e32 v9, v97, v131
	ds_write2_b32 v153, v0, v32 offset0:192 offset1:224
	v_mul_f32_e32 v0, v116, v131
	v_mul_f32_e32 v9, v9, v151
	v_mul_f32_e32 v0, v0, v152
	v_mul_f32_e32 v16, v98, v133
	ds_write2_b32 v23, v9, v0 offset0:192 offset1:224
	v_mul_f32_e32 v0, v115, v133
	v_mul_f32_e32 v16, v16, v151
	v_mul_f32_e32 v0, v0, v152
	v_mul_f32_e32 v17, v99, v135
	ds_write2_b32 v21, v16, v0 offset0:192 offset1:224
	v_mul_f32_e32 v0, v114, v135
	v_mul_f32_e32 v17, v17, v151
	v_mul_f32_e32 v0, v0, v152
	v_mul_f32_e32 v18, v100, v137
	ds_write2_b32 v10, v17, v0 offset0:192 offset1:224
	v_mul_f32_e32 v0, v113, v137
	v_mul_f32_e32 v18, v18, v151
	v_mul_f32_e32 v0, v0, v152
	v_mul_f32_e32 v19, v101, v139
	ds_write2_b32 v7, v18, v0 offset0:192 offset1:224
	v_mul_f32_e32 v0, v119, v139
	v_mul_f32_e32 v19, v19, v151
	v_mul_f32_e32 v0, v0, v152
	v_mul_f32_e32 v20, v102, v141
	ds_write2_b32 v5, v19, v0 offset0:192 offset1:224
	v_mul_f32_e32 v0, v118, v141
	v_mul_f32_e32 v20, v20, v151
	v_mul_f32_e32 v0, v0, v152
	v_mul_f32_e32 v22, v103, v142
	ds_write2_b32 v4, v20, v0 offset0:192 offset1:224
	v_mul_f32_e32 v0, v120, v142
	v_mul_f32_e32 v22, v22, v151
	v_mul_f32_e32 v0, v0, v152
	v_mul_f32_e32 v24, v104, v140
	ds_write2_b32 v2, v22, v0 offset0:192 offset1:224
	v_mul_f32_e32 v0, v121, v140
	v_mul_f32_e32 v24, v24, v151
	v_mul_f32_e32 v0, v0, v152
	v_mul_f32_e32 v25, v105, v138
	ds_write2_b32 v3, v24, v0 offset0:192 offset1:224
	v_mul_f32_e32 v0, v124, v138
	v_mul_f32_e32 v25, v25, v151
	v_mul_f32_e32 v0, v0, v152
	v_mul_f32_e32 v26, v106, v136
	ds_write2_b32 v15, v25, v0 offset0:192 offset1:224
	v_mul_f32_e32 v0, v122, v136
	v_mul_f32_e32 v26, v26, v151
	v_mul_f32_e32 v0, v0, v152
	v_mul_f32_e32 v27, v107, v134
	ds_write2_b32 v14, v26, v0 offset0:192 offset1:224
	v_mul_f32_e32 v0, v125, v134
	v_mul_f32_e32 v27, v27, v151
	v_mul_f32_e32 v0, v0, v152
	v_mul_f32_e32 v28, v108, v132
	ds_write2_b32 v13, v27, v0 offset0:192 offset1:224
	v_mul_f32_e32 v0, v123, v132
	v_mul_f32_e32 v28, v28, v151
	v_mul_f32_e32 v0, v0, v152
	v_mul_f32_e32 v29, v109, v130
	ds_write2_b32 v12, v28, v0 offset0:192 offset1:224
	v_mul_f32_e32 v0, v127, v130
	v_mul_f32_e32 v29, v29, v151
	v_mul_f32_e32 v0, v0, v152
	v_mul_f32_e32 v30, v110, v143
	ds_write2_b32 v11, v29, v0 offset0:192 offset1:224
	v_mul_f32_e32 v0, v126, v143
	v_mul_f32_e32 v30, v30, v151
	v_mul_f32_e32 v0, v0, v152
	v_mul_f32_e32 v31, v111, v144
	ds_write2_b32 v8, v30, v0 offset0:192 offset1:224
	v_mul_f32_e32 v0, v128, v144
	v_mul_f32_e32 v31, v31, v151
	v_mul_f32_e32 v0, v0, v152
	ds_write2_b32 v6, v31, v0 offset0:192 offset1:224
	v_mov_b32_e32 v0, v220
	s_mov_b64 s[2:3], 0
	v_ashrrev_i32_e32 v4, 5, v0
	v_ashrrev_i32_e32 v5, 31, v4
	v_lshl_add_u64 v[2:3], v[4:5], 0, s[4:5]
	v_lshlrev_b32_e32 v5, 4, v0
	v_lshlrev_b64 v[2:3], 12, v[2:3]
	v_and_b32_e32 v5, 0x1f0, v5
	v_and_b32_e32 v0, 31, v0
	v_or3_b32 v2, s0, v5, v2
	v_lshl_add_u32 v4, v4, 10, s38
	v_lshlrev_b32_e32 v0, 5, v0
	v_lshl_add_u64 v[2:3], s[80:81], 0, v[2:3]
	v_add3_u32 v0, v4, v0, 0

.LBB0_813:
	global_load_dwordx4 v[112:115], v[36:37], off offset:1024
	global_load_dwordx4 v[116:119], v[36:37], off offset:2048
	global_load_dwordx4 v[120:123], v[36:37], off offset:3072
	global_load_dwordx4 v[124:127], v[38:39], off
	global_load_dwordx4 v[128:131], v[40:41], off
	global_load_dwordx4 v[132:135], v[42:43], off
	global_load_dwordx4 v[136:139], v[44:45], off
	s_lshl_b32 s29, s28, 6
	s_mov_b32 s30, 0
	s_branch .LBB0_815

.LBB0_815:
	s_add_i32 s31, s30, s17
	s_add_i32 s0, s31, s29
	s_ashr_i32 s1, s0, 31
	s_lshl_b64 s[34:35], s[0:1], 13
	v_lshl_add_u64 v[0:1], v[30:31], 0, s[34:35]
	global_load_dwordx4 v[46:49], v[0:1], off
	global_load_dwordx4 v[8:11], v[0:1], off offset:1024
	global_load_dwordx4 v[24:27], v[0:1], off offset:2048
	global_load_dwordx4 v[16:19], v[0:1], off offset:3072
	v_add_co_u32_e32 v12, vcc, s18, v0
	s_lshl_b64 s[34:35], s[0:1], 12
	s_nop 0
	v_addc_co_u32_e32 v13, vcc, 0, v1, vcc
	global_load_dwordx4 v[4:7], v[12:13], off
	global_load_dwordx4 v[20:23], v[12:13], off offset:1024
	global_load_dwordx4 v[0:3], v[12:13], off offset:3072
	s_nop 0
	global_load_dwordx4 v[12:15], v[12:13], off offset:2048
	s_nop 0
	global_load_dwordx4 v[70:73], v[36:37], off
	s_waitcnt vmcnt(8)
	v_mov_b32_e32 v76, v47
	s_waitcnt vmcnt(7)
	v_mov_b32_e32 v77, v9
	v_mov_b32_e32 v80, v49
	v_mov_b32_e32 v81, v11
	v_mov_b32_e32 v74, v46
	v_mov_b32_e32 v75, v8
	v_mov_b32_e32 v78, v48
	v_mov_b32_e32 v79, v10
	s_waitcnt vmcnt(6)
	v_pk_mul_f32 v[82:83], v[26:27], v[26:27]
	v_pk_mul_f32 v[84:85], v[24:25], v[24:25]
	v_pk_mul_f32 v[76:77], v[76:77], v[76:77]
	v_pk_mul_f32 v[80:81], v[80:81], v[80:81]
	v_pk_mov_b32 v[90:91], v[84:85], v[82:83] op_sel:[1,0]
	v_mov_b32_e32 v85, v83
	v_pk_fma_f32 v[74:75], v[74:75], v[74:75], v[76:77]
	v_pk_fma_f32 v[76:77], v[78:79], v[78:79], v[80:81]
	s_waitcnt vmcnt(5)
	v_mul_f32_e32 v86, v17, v17
	v_mul_f32_e32 v88, v19, v19
	v_pk_add_f32 v[78:79], v[90:91], v[84:85]
	v_pk_add_f32 v[74:75], v[74:75], v[76:77]
	s_waitcnt vmcnt(4)
	v_mul_f32_e32 v95, v4, v4
	v_mul_f32_e32 v97, v5, v5
	v_mul_f32_e32 v98, v6, v6
	v_mul_f32_e32 v99, v7, v7
	v_pk_fma_f32 v[82:83], v[16:17], v[16:17], v[86:87] op_sel_hi:[1,1,0]
	v_pk_fma_f32 v[86:87], v[18:19], v[18:19], v[88:89] op_sel_hi:[1,1,0]
	v_pk_add_f32 v[76:77], v[78:79], v[78:79] op_sel:[0,1] op_sel_hi:[1,0]
	v_pk_add_f32 v[74:75], v[74:75], v[74:75] op_sel:[0,1] op_sel_hi:[1,0]
	s_waitcnt vmcnt(3)
	v_pk_mul_f32 v[88:89], v[22:23], v[22:23]
	v_pk_mul_f32 v[92:93], v[20:21], v[20:21]
	v_mov_b32_e32 v83, v98
	v_mov_b32_e32 v87, v99
	v_mov_b32_e32 v77, v97
	v_mov_b32_e32 v75, v95
	v_pk_mov_b32 v[80:81], v[92:93], v[88:89] op_sel:[1,0]
	v_mov_b32_e32 v93, v89
	v_pk_add_f32 v[78:79], v[82:83], v[86:87]
	v_pk_add_f32 v[74:75], v[74:75], v[76:77]
	s_waitcnt vmcnt(1)
	v_mul_f32_e32 v94, v13, v13
	v_mul_f32_e32 v96, v15, v15
	v_pk_add_f32 v[80:81], v[80:81], v[92:93]
	v_pk_add_f32 v[74:75], v[74:75], v[78:79]
	v_mul_f32_e32 v100, v0, v0
	v_mul_f32_e32 v101, v1, v1
	v_mul_f32_e32 v102, v2, v2
	v_mul_f32_e32 v103, v3, v3
	v_pk_fma_f32 v[84:85], v[12:13], v[12:13], v[94:95] op_sel_hi:[1,1,0]
	v_pk_fma_f32 v[88:89], v[14:15], v[14:15], v[96:97] op_sel_hi:[1,1,0]
	v_pk_add_f32 v[80:81], v[80:81], v[80:81] op_sel:[0,1] op_sel_hi:[1,0]
	v_pk_add_f32 v[74:75], v[74:75], v[74:75] op_sel:[0,1] op_sel_hi:[1,0]
	v_mov_b32_e32 v85, v102
	v_mov_b32_e32 v89, v103
	v_mov_b32_e32 v81, v101
	v_mov_b32_e32 v75, v100
	v_pk_add_f32 v[82:83], v[84:85], v[88:89]
	v_pk_add_f32 v[74:75], v[74:75], v[80:81]
	s_nop 0
	v_pk_add_f32 v[74:75], v[74:75], v[82:83]
	s_nop 0
	v_add_f32_e32 v74, v74, v75
	s_waitcnt lgkmcnt(0)
	s_nop 1
	v_add_f32_dpp v74, v74, v74 quad_perm:[1,0,3,2] row_mask:0xf bank_mask:0xf
	s_waitcnt lgkmcnt(0)
	s_nop 1
	v_add_f32_dpp v74, v74, v74 quad_perm:[2,3,0,1] row_mask:0xf bank_mask:0xf
	s_waitcnt lgkmcnt(0)
	s_nop 1
	v_add_f32_dpp v74, v74, v74 row_half_mirror row_mask:0xf bank_mask:0xf
	s_waitcnt lgkmcnt(0)
	s_nop 1
	v_add_f32_dpp v74, v74, v74 row_mirror row_mask:0xf bank_mask:0xf
	s_waitcnt lgkmcnt(0)
	v_mov_b32_e32 v75, v74
	s_nop 1
	v_permlane16_swap_b32_e32 v74, v75
	v_add_f32_e32 v74, v74, v75
	s_waitcnt lgkmcnt(0)
	v_mov_b32_e32 v75, v74
	s_nop 1
	v_permlane32_swap_b32_e32 v74, v75
	v_add_f32_e32 v74, v74, v75
	v_fmamk_f32 v74, v74, 0x3a000000, v66
	v_mul_f32_e32 v75, 0x4f800000, v74
	v_cmp_gt_f32_e32 vcc, s19, v74
	s_nop 1
	v_cndmask_b32_e32 v74, v74, v75, vcc
	v_sqrt_f32_e32 v75, v74
	s_nop 0
	v_add_u32_e32 v76, -1, v75
	v_add_u32_e32 v77, 1, v75
	v_fma_f32 v78, -v76, v75, v74
	v_fma_f32 v79, -v77, v75, v74
	v_cmp_ge_f32_e64 s[0:1], 0, v78
	s_nop 1
	v_cndmask_b32_e64 v75, v75, v76, s[0:1]
	v_cmp_lt_f32_e64 s[0:1], 0, v79
	s_nop 1
	v_cndmask_b32_e64 v75, v75, v77, s[0:1]
	v_mul_f32_e32 v76, 0x37800000, v75
	v_cndmask_b32_e32 v75, v75, v76, vcc
	v_cmp_class_f32_e32 vcc, v74, v67
	v_lshl_add_u64 v[76:77], v[32:33], 0, s[34:35]
	s_nop 0
	v_cndmask_b32_e32 v74, v75, v74, vcc
	v_div_scale_f32 v75, s[0:1], v74, v74, 1.0
	v_rcp_f32_e32 v78, v75
	v_div_scale_f32 v79, vcc, 1.0, v74, 1.0
	s_mov_b32 s0, 0
	v_fma_f32 v80, -v75, v78, 1.0
	v_fmac_f32_e32 v78, v80, v78
	v_mul_f32_e32 v80, v79, v78
	v_fma_f32 v81, -v75, v80, v79
	v_fmac_f32_e32 v80, v81, v78
	v_fma_f32 v75, -v75, v80, v79
	v_div_fmas_f32 v75, v75, v78, v80
	v_div_fixup_f32 v78, v75, v74, 1.0
	v_pk_mul_f32 v[46:47], v[46:47], v[78:79] op_sel_hi:[1,0]
	v_pk_mul_f32 v[48:49], v[48:49], v[78:79] op_sel_hi:[1,0]
	s_waitcnt vmcnt(0)
	v_pk_mul_f32 v[82:83], v[70:71], v[46:47]
	v_pk_mul_f32 v[80:81], v[72:73], v[48:49]
	v_cvt_pk_bf16_f32 v46, v82, v83
	v_cvt_pk_bf16_f32 v47, v80, v81
	global_store_dwordx2 v[76:77], v[46:47], off
	v_pk_mul_f32 v[70:71], v[8:9], v[78:79] op_sel_hi:[1,0]
	v_pk_mul_f32 v[8:9], v[10:11], v[78:79] op_sel_hi:[1,0]
	v_pk_mul_f32 v[26:27], v[26:27], v[78:79] op_sel_hi:[1,0]
	v_pk_mul_f32 v[24:25], v[24:25], v[78:79] op_sel_hi:[1,0]
	v_pk_mul_f32 v[18:19], v[18:19], v[78:79] op_sel_hi:[1,0]
	v_pk_mul_f32 v[16:17], v[16:17], v[78:79] op_sel_hi:[1,0]
	v_pk_mul_f32 v[22:23], v[22:23], v[78:79] op_sel_hi:[1,0]
	v_pk_mul_f32 v[20:21], v[20:21], v[78:79] op_sel_hi:[1,0]
	v_pk_mul_f32 v[14:15], v[14:15], v[78:79] op_sel_hi:[1,0]
	v_pk_mul_f32 v[12:13], v[12:13], v[78:79] op_sel_hi:[1,0]
	v_pk_mul_f32 v[8:9], v[114:115], v[8:9]
	v_pk_mul_f32 v[10:11], v[112:113], v[70:71]
	v_cvt_pk_bf16_f32 v47, v8, v9
	v_cvt_pk_bf16_f32 v46, v10, v11
	global_store_dwordx2 v[76:77], v[46:47], off offset:512
	v_pk_mul_f32 v[70:71], v[4:5], v[78:79] op_sel_hi:[1,0]
	v_pk_mul_f32 v[4:5], v[6:7], v[78:79] op_sel_hi:[1,0]
	v_pk_mul_f32 v[24:25], v[116:117], v[24:25]
	v_pk_mul_f32 v[26:27], v[118:119], v[26:27]
	v_cvt_pk_bf16_f32 v46, v24, v25
	v_cvt_pk_bf16_f32 v47, v26, v27
	global_store_dwordx2 v[76:77], v[46:47], off offset:1024
	v_pk_mul_f32 v[16:17], v[120:121], v[16:17]
	v_pk_mul_f32 v[18:19], v[122:123], v[18:19]
	v_cvt_pk_bf16_f32 v46, v16, v17
	v_cvt_pk_bf16_f32 v47, v18, v19
	global_store_dwordx2 v[76:77], v[46:47], off offset:1536
	v_pk_mul_f32 v[4:5], v[126:127], v[4:5]
	v_pk_mul_f32 v[6:7], v[124:125], v[70:71]
	v_cvt_pk_bf16_f32 v47, v4, v5
	v_cvt_pk_bf16_f32 v46, v6, v7
	global_store_dwordx2 v[76:77], v[46:47], off offset:2048
	v_mov_b32_e32 v70, 0
	v_pk_mul_f32 v[20:21], v[128:129], v[20:21]
	v_pk_mul_f32 v[22:23], v[130:131], v[22:23]
	v_cvt_pk_bf16_f32 v46, v20, v21
	v_cvt_pk_bf16_f32 v47, v22, v23
	global_store_dwordx2 v[76:77], v[46:47], off offset:2560
	v_pk_mul_f32 v[12:13], v[12:13], v[132:133]
	v_pk_mul_f32 v[14:15], v[14:15], v[134:135]
	v_cvt_pk_bf16_f32 v46, v12, v13
	v_cvt_pk_bf16_f32 v47, v14, v15
	global_store_dwordx2 v[76:77], v[46:47], off offset:3072
	v_pk_mul_f32 v[48:49], v[0:1], v[78:79] op_sel_hi:[1,0]
	v_pk_mul_f32 v[46:47], v[2:3], v[78:79] op_sel_hi:[1,0]
	v_mov_b32_e32 v0, v82
	v_mov_b32_e32 v2, v80
	v_mov_b32_e32 v1, v10
	v_mov_b32_e32 v10, v83
	v_mov_b32_e32 v3, v8
	v_mov_b32_e32 v8, v81
	v_pk_mul_f32 v[46:47], v[46:47], v[138:139]
	v_pk_mul_f32 v[48:49], v[48:49], v[136:137]
	v_cvt_pk_bf16_f32 v73, v46, v47
	v_cvt_pk_bf16_f32 v72, v48, v49
	global_store_dwordx2 v[76:77], v[72:73], off offset:3584
.LBB0_816:
	v_add_u32_e32 v71, s0, v57
	ds_read_b128 v[72:75], v71
	ds_read_b128 v[76:79], v71 offset:1024
	ds_read_b128 v[80:83], v71 offset:2048
	ds_read_b128 v[84:87], v71 offset:3072
	ds_read_b128 v[88:91], v71 offset:4096
	ds_read_b128 v[92:95], v71 offset:5120
	ds_read_b128 v[96:99], v71 offset:6144
	ds_read_b128 v[100:103], v71 offset:7168
	s_waitcnt lgkmcnt(6)
	v_mov_b32_e32 v105, v76
	v_mov_b32_e32 v76, v73
	v_mov_b32_e32 v73, v78
	v_mov_b32_e32 v78, v75
	v_mov_b32_e32 v104, v72
	v_mov_b32_e32 v72, v74
	s_waitcnt lgkmcnt(5)
	v_pk_mul_f32 v[74:75], v[26:27], v[82:83]
	v_pk_mul_f32 v[80:81], v[24:25], v[80:81]
	v_pk_mul_f32 v[76:77], v[10:11], v[76:77]
	v_pk_mul_f32 v[78:79], v[8:9], v[78:79]
	s_waitcnt lgkmcnt(0)
	v_mul_f32_e32 v108, v46, v102
	v_mul_f32_e32 v109, v47, v103
	v_pk_mov_b32 v[102:103], v[80:81], v[74:75] op_sel:[1,0]
	v_mov_b32_e32 v81, v75
	v_pk_fma_f32 v[76:77], v[0:1], v[104:105], v[76:77]
	v_pk_fma_f32 v[72:73], v[2:3], v[72:73], v[78:79]
	v_mul_f32_e32 v83, v6, v88
	v_mul_f32_e32 v82, v17, v85
	v_mul_f32_e32 v88, v19, v87
	v_pk_add_f32 v[78:79], v[102:103], v[80:81]
	v_pk_add_f32 v[72:73], v[76:77], v[72:73]
	v_mul_f32_e32 v71, v7, v89
	v_mul_f32_e32 v106, v4, v90
	v_mul_f32_e32 v107, v5, v91
	v_pk_fma_f32 v[74:75], v[16:17], v[84:85], v[82:83] op_sel_hi:[1,1,0]
	v_pk_fma_f32 v[84:85], v[18:19], v[86:87], v[88:89] op_sel_hi:[1,1,0]
	v_pk_add_f32 v[76:77], v[78:79], v[78:79] op_sel:[0,1] op_sel_hi:[1,0]
	v_add_f32_e32 v72, 0, v72
	v_pk_mul_f32 v[90:91], v[22:23], v[94:95]
	v_pk_mul_f32 v[92:93], v[20:21], v[92:93]
	v_mov_b32_e32 v75, v106
	v_mov_b32_e32 v85, v107
	v_mov_b32_e32 v77, v71
	v_add_f32_e32 v82, v72, v73
	v_pk_mov_b32 v[86:87], v[92:93], v[90:91] op_sel:[1,0]
	v_mov_b32_e32 v93, v91
	v_pk_add_f32 v[74:75], v[74:75], v[84:85]
	v_pk_add_f32 v[72:73], v[82:83], v[76:77]
	v_mul_f32_e32 v95, v48, v100
	v_mul_f32_e32 v101, v49, v101
	v_mul_f32_e32 v94, v13, v97
	v_mul_f32_e32 v100, v15, v99
	v_pk_add_f32 v[80:81], v[86:87], v[92:93]
	v_pk_add_f32 v[72:73], v[72:73], v[74:75]
	v_pk_fma_f32 v[88:89], v[12:13], v[96:97], v[94:95] op_sel_hi:[1,1,0]
	v_pk_fma_f32 v[90:91], v[14:15], v[98:99], v[100:101] op_sel_hi:[1,1,0]
	v_pk_add_f32 v[78:79], v[80:81], v[80:81] op_sel:[0,1] op_sel_hi:[1,0]
	v_pk_add_f32 v[72:73], v[72:73], v[72:73] op_sel:[0,1] op_sel_hi:[1,0]
	v_mov_b32_e32 v89, v108
	v_mov_b32_e32 v91, v109
	v_mov_b32_e32 v79, v101
	v_mov_b32_e32 v73, v95
	v_pk_add_f32 v[80:81], v[88:89], v[90:91]
	v_pk_add_f32 v[72:73], v[72:73], v[78:79]
	v_cmp_eq_u32_e32 vcc, s0, v65
	v_pk_add_f32 v[72:73], v[72:73], v[80:81]
	s_addk_i32 s0, 0x2000
	v_add_f32_e32 v71, v72, v73
	s_cmp_lg_u32 s0, 0x20000
	s_waitcnt lgkmcnt(0)
	s_nop 1
	v_add_f32_dpp v71, v71, v71 quad_perm:[1,0,3,2] row_mask:0xf bank_mask:0xf
	s_waitcnt lgkmcnt(0)
	s_nop 1
	v_add_f32_dpp v71, v71, v71 quad_perm:[2,3,0,1] row_mask:0xf bank_mask:0xf
	s_waitcnt lgkmcnt(0)
	s_nop 1
	v_add_f32_dpp v71, v71, v71 row_half_mirror row_mask:0xf bank_mask:0xf
	s_waitcnt lgkmcnt(0)
	s_nop 1
	v_add_f32_dpp v71, v71, v71 row_mirror row_mask:0xf bank_mask:0xf
	s_waitcnt lgkmcnt(0)
	v_mov_b32_e32 v72, v71
	s_nop 1
	v_permlane16_swap_b32_e32 v71, v72
	v_add_f32_e32 v71, v71, v72
	s_waitcnt lgkmcnt(0)
	v_mov_b32_e32 v72, v71
	s_nop 1
	v_permlane32_swap_b32_e32 v71, v72
	v_add_f32_e32 v71, v71, v72
	v_cndmask_b32_e32 v70, v70, v71, vcc
	s_cbranch_scc1 .LBB0_816
	s_and_saveexec_b64 s[0:1], s[2:3]
	s_cbranch_execz .LBB0_814
	global_load_dword v0, v[34:35], off
	v_lshl_add_u32 v1, s31, 6, v58
	s_waitcnt vmcnt(0)
	v_add_f32_e32 v0, v70, v0
	ds_write_b32 v1, v0
	s_branch .LBB0_814

.LBB0_1623:
	s_andn2_b64 vcc, exec, s[0:1]
	s_waitcnt lgkmcnt(0)
	s_barrier
	s_cbranch_vccnz .LBB0_1590
	ds_read2st64_b32 v[4:5], v143 offset1:1
	ds_read2st64_b32 v[12:13], v143 offset0:2 offset1:3
	ds_read2st64_b32 v[14:15], v143 offset0:4 offset1:5
	ds_read2st64_b32 v[16:17], v143 offset0:6 offset1:7
	s_lshl_b32 s0, s48, 6
	s_and_b32 s4, s0, 0x2000
	s_waitcnt lgkmcnt(2)
	v_sub_f32_e32 v7, v135, v12
	v_sub_f32_e32 v112, v0, v4
	v_sub_f32_e32 v10, v134, v5
	v_sub_f32_e32 v5, v136, v13
	s_waitcnt lgkmcnt(1)
	v_sub_f32_e32 v4, v2, v14
	v_sub_f32_e32 v2, v20, v15
	s_waitcnt lgkmcnt(0)
	v_sub_f32_e32 v0, v21, v16
	ds_read2st64_b32 v[12:13], v143 offset0:8 offset1:9
	v_sub_f32_e32 v3, v3, v17
	ds_read2st64_b32 v[16:17], v143 offset0:10 offset1:11
	ds_read2st64_b32 v[20:21], v143 offset0:12 offset1:13
	ds_read2st64_b32 v[30:31], v143 offset0:14 offset1:15
	s_waitcnt lgkmcnt(3)
	v_sub_f32_e32 v15, v6, v12
	v_sub_f32_e32 v14, v8, v13
	s_waitcnt lgkmcnt(2)
	v_sub_f32_e32 v13, v9, v16
	v_sub_f32_e32 v12, v22, v17
	s_waitcnt lgkmcnt(1)
	v_sub_f32_e32 v8, v28, v21
	s_waitcnt lgkmcnt(0)
	v_sub_f32_e32 v6, v29, v30
	ds_read2st64_b32 v[16:17], v143 offset0:16 offset1:17
	v_sub_f32_e32 v9, v23, v31
	ds_read2st64_b32 v[28:29], v143 offset0:18 offset1:19
	ds_read2st64_b32 v[30:31], v143 offset0:20 offset1:21
	ds_read2st64_b32 v[32:33], v143 offset0:22 offset1:23
	v_sub_f32_e32 v11, v11, v20
	s_waitcnt lgkmcnt(3)
	v_sub_f32_e32 v22, v133, v16
	v_sub_f32_e32 v23, v132, v17
	s_waitcnt lgkmcnt(2)
	v_sub_f32_e32 v21, v131, v28
	v_sub_f32_e32 v20, v130, v29
	s_waitcnt lgkmcnt(0)
	v_sub_f32_e32 v16, v35, v32
	v_sub_f32_e32 v17, v34, v33
	ds_read2st64_b32 v[28:29], v143 offset0:24 offset1:25
	ds_read2st64_b32 v[32:33], v143 offset0:26 offset1:27
	ds_read2st64_b32 v[34:35], v143 offset0:28 offset1:29
	ds_read2st64_b32 v[46:47], v143 offset0:30 offset1:31
	v_sub_f32_e32 v19, v19, v30
	v_sub_f32_e32 v18, v18, v31
	v_mul_f32_e32 v151, v22, v22
	s_waitcnt lgkmcnt(3)
	v_sub_f32_e32 v31, v39, v28
	v_sub_f32_e32 v30, v38, v29
	s_waitcnt lgkmcnt(2)
	v_sub_f32_e32 v29, v25, v32
	v_sub_f32_e32 v28, v24, v33
	s_waitcnt lgkmcnt(1)
	v_sub_f32_e32 v27, v27, v34
	v_sub_f32_e32 v26, v26, v35
	s_waitcnt lgkmcnt(0)
	v_sub_f32_e32 v24, v43, v46
	v_sub_f32_e32 v25, v42, v47
	ds_read2st64_b32 v[32:33], v143 offset0:32 offset1:33
	ds_read2st64_b32 v[34:35], v143 offset0:34 offset1:35
	ds_read2st64_b32 v[38:39], v143 offset0:36 offset1:37
	ds_read2st64_b32 v[42:43], v143 offset0:38 offset1:39
	v_fmac_f32_e32 v151, v112, v112
	v_mul_f32_e32 v148, v23, v23
	v_fmac_f32_e32 v148, v10, v10
	s_waitcnt lgkmcnt(1)
	v_sub_f32_e32 v36, v36, v38
	v_sub_f32_e32 v37, v37, v39
	s_waitcnt lgkmcnt(0)
	v_sub_f32_e32 v38, v53, v42
	v_sub_f32_e32 v39, v52, v43
	ds_read2st64_b32 v[42:43], v143 offset0:40 offset1:41
	ds_read2st64_b32 v[46:47], v143 offset0:42 offset1:43
	ds_read2st64_b32 v[48:49], v143 offset0:44 offset1:45
	ds_read2st64_b32 v[52:53], v143 offset0:46 offset1:47
	v_sub_f32_e32 v32, v161, v32
	v_fmac_f32_e32 v151, v32, v32
	v_sub_f32_e32 v33, v160, v33
	s_waitcnt lgkmcnt(3)
	v_sub_f32_e32 v40, v40, v42
	v_sub_f32_e32 v41, v41, v43
	s_waitcnt lgkmcnt(2)
	v_sub_f32_e32 v42, v55, v46
	v_sub_f32_e32 v43, v54, v47
	s_waitcnt lgkmcnt(1)
	v_sub_f32_e32 v44, v44, v48
	v_sub_f32_e32 v45, v45, v49
	s_waitcnt lgkmcnt(0)
	v_sub_f32_e32 v46, v61, v52
	v_sub_f32_e32 v47, v60, v53
	ds_read2st64_b32 v[48:49], v143 offset0:48 offset1:49
	ds_read2st64_b32 v[60:61], v143 offset0:50 offset1:51
	ds_read2st64_b32 v[62:63], v143 offset0:52 offset1:53
	ds_read2st64_b32 v[64:65], v143 offset0:54 offset1:55
	v_fmac_f32_e32 v148, v33, v33
	v_mul_f32_e32 v144, v21, v21
	s_waitcnt lgkmcnt(2)
	v_sub_f32_e32 v53, v153, v60
	v_sub_f32_e32 v55, v155, v48
	v_sub_f32_e32 v54, v154, v49
	v_sub_f32_e32 v52, v152, v61
	s_waitcnt lgkmcnt(0)
	v_sub_f32_e32 v48, v87, v64
	v_sub_f32_e32 v49, v86, v65
	ds_read2st64_b32 v[60:61], v143 offset0:56 offset1:57
	ds_read2st64_b32 v[64:65], v143 offset0:58 offset1:59
	ds_read2st64_b32 v[86:87], v143 offset0:60 offset1:61
	ds_read2st64_b32 v[152:153], v143 offset0:62 offset1:63
	v_sub_f32_e32 v51, v51, v62
	v_sub_f32_e32 v50, v50, v63
	v_fmac_f32_e32 v151, v55, v55
	s_waitcnt lgkmcnt(3)
	v_sub_f32_e32 v63, v157, v60
	v_sub_f32_e32 v62, v156, v61
	s_waitcnt lgkmcnt(2)
	v_sub_f32_e32 v61, v57, v64
	v_sub_f32_e32 v60, v56, v65
	s_waitcnt lgkmcnt(1)
	v_sub_f32_e32 v59, v59, v86
	v_sub_f32_e32 v58, v58, v87
	s_waitcnt lgkmcnt(0)
	v_sub_f32_e32 v56, v95, v152
	v_sub_f32_e32 v57, v94, v153
	ds_read2st64_b32 v[64:65], v143 offset0:64 offset1:65
	ds_read2st64_b32 v[86:87], v143 offset0:66 offset1:67
	ds_read2st64_b32 v[94:95], v143 offset0:68 offset1:69
	ds_read2st64_b32 v[152:153], v143 offset0:70 offset1:71
	v_fmac_f32_e32 v148, v54, v54
	v_fmac_f32_e32 v144, v7, v7
	s_waitcnt lgkmcnt(2)
	v_sub_f32_e32 v66, v66, v86
	v_sub_f32_e32 v64, v69, v64
	v_sub_f32_e32 v65, v68, v65
	v_sub_f32_e32 v67, v67, v87
	s_waitcnt lgkmcnt(1)
	v_sub_f32_e32 v68, v73, v94
	v_sub_f32_e32 v69, v72, v95
	s_waitcnt lgkmcnt(0)
	v_sub_f32_e32 v70, v70, v152
	v_sub_f32_e32 v71, v71, v153
	ds_read2st64_b32 v[72:73], v143 offset0:72 offset1:73
	ds_read2st64_b32 v[86:87], v143 offset0:74 offset1:75
	ds_read2st64_b32 v[94:95], v143 offset0:76 offset1:77
	ds_read2st64_b32 v[152:153], v143 offset0:78 offset1:79
	v_fmac_f32_e32 v151, v64, v64
	v_fmac_f32_e32 v148, v65, v65
	s_waitcnt lgkmcnt(2)
	v_sub_f32_e32 v74, v74, v86
	v_sub_f32_e32 v72, v77, v72
	v_sub_f32_e32 v73, v76, v73
	s_waitcnt lgkmcnt(1)
	v_sub_f32_e32 v76, v81, v94
	v_sub_f32_e32 v77, v80, v95
	s_waitcnt lgkmcnt(0)
	v_sub_f32_e32 v78, v78, v152
	v_sub_f32_e32 v79, v79, v153
	ds_read2st64_b32 v[80:81], v143 offset0:80 offset1:81
	ds_read2st64_b32 v[94:95], v143 offset0:82 offset1:83
	ds_read2st64_b32 v[152:153], v143 offset0:84 offset1:85
	ds_read2st64_b32 v[154:155], v143 offset0:86 offset1:87
	v_sub_f32_e32 v75, v75, v87
	v_sub_f32_e32 v34, v159, v34
	v_fmac_f32_e32 v144, v34, v34
	s_waitcnt lgkmcnt(3)
	v_sub_f32_e32 v87, v85, v80
	v_sub_f32_e32 v86, v84, v81
	s_waitcnt lgkmcnt(2)
	v_sub_f32_e32 v85, v83, v94
	v_sub_f32_e32 v84, v82, v95
	s_waitcnt lgkmcnt(1)
	v_sub_f32_e32 v83, v147, v152
	v_sub_f32_e32 v82, v146, v153
	s_waitcnt lgkmcnt(0)
	v_sub_f32_e32 v80, v89, v154
	v_sub_f32_e32 v81, v88, v155
	ds_read2st64_b32 v[88:89], v143 offset0:88 offset1:89
	ds_read2st64_b32 v[146:147], v143 offset0:90 offset1:91
	ds_read2st64_b32 v[152:153], v143 offset0:92 offset1:93
	ds_read2st64_b32 v[154:155], v143 offset0:94 offset1:95
	v_fmac_f32_e32 v151, v87, v87
	v_fmac_f32_e32 v148, v86, v86
	v_fmac_f32_e32 v144, v53, v53
	s_waitcnt lgkmcnt(3)
	v_sub_f32_e32 v95, v93, v88
	v_sub_f32_e32 v94, v92, v89
	s_waitcnt lgkmcnt(2)
	v_sub_f32_e32 v93, v91, v146
	v_sub_f32_e32 v92, v90, v147
	s_waitcnt lgkmcnt(1)
	v_sub_f32_e32 v91, v150, v152
	v_sub_f32_e32 v90, v149, v153
	s_waitcnt lgkmcnt(0)
	v_sub_f32_e32 v88, v97, v154
	v_sub_f32_e32 v89, v96, v155
	ds_read2st64_b32 v[96:97], v143 offset0:96 offset1:97
	ds_read2st64_b32 v[146:147], v143 offset0:98 offset1:99
	ds_read2st64_b32 v[152:153], v143 offset0:100 offset1:101
	ds_read2st64_b32 v[154:155], v143 offset0:102 offset1:103
	v_fmac_f32_e32 v144, v66, v66
	v_fmac_f32_e32 v144, v85, v85
	s_waitcnt lgkmcnt(2)
	v_sub_f32_e32 v98, v98, v146
	v_sub_f32_e32 v96, v101, v96
	v_sub_f32_e32 v97, v100, v97
	v_sub_f32_e32 v99, v99, v147
	s_waitcnt lgkmcnt(1)
	v_sub_f32_e32 v100, v105, v152
	v_sub_f32_e32 v101, v104, v153
	s_waitcnt lgkmcnt(0)
	v_sub_f32_e32 v102, v102, v154
	v_sub_f32_e32 v103, v103, v155
	ds_read2st64_b32 v[104:105], v143 offset0:104 offset1:105
	ds_read2st64_b32 v[146:147], v143 offset0:106 offset1:107
	ds_read2st64_b32 v[152:153], v143 offset0:108 offset1:109
	ds_read2st64_b32 v[154:155], v143 offset0:110 offset1:111
	v_fmac_f32_e32 v151, v96, v96
	v_fmac_f32_e32 v148, v97, v97
	s_waitcnt lgkmcnt(2)
	v_sub_f32_e32 v106, v106, v146
	v_sub_f32_e32 v107, v107, v147
	ds_read2st64_b32 v[146:147], v143 offset0:112 offset1:113
	v_sub_f32_e32 v104, v109, v104
	v_sub_f32_e32 v105, v108, v105
	s_waitcnt lgkmcnt(2)
	v_sub_f32_e32 v108, v145, v152
	v_sub_f32_e32 v109, v113, v153
	s_waitcnt lgkmcnt(1)
	v_sub_f32_e32 v110, v110, v154
	v_sub_f32_e32 v111, v111, v155
	ds_read2st64_b32 v[152:153], v143 offset0:114 offset1:115
	ds_read2st64_b32 v[154:155], v143 offset0:116 offset1:117
	ds_read2st64_b32 v[156:157], v143 offset0:118 offset1:119
	s_waitcnt lgkmcnt(3)
	v_sub_f32_e32 v117, v117, v146
	v_fmac_f32_e32 v151, v117, v117
	v_sub_f32_e32 v116, v116, v147
	s_waitcnt lgkmcnt(1)
	v_sub_f32_e32 v113, v121, v154
	ds_read2st64_b32 v[146:147], v143 offset0:120 offset1:121
	v_sub_f32_e32 v115, v115, v152
	v_sub_f32_e32 v114, v114, v153
	v_sub_f32_e32 v119, v119, v155
	s_waitcnt lgkmcnt(1)
	s_nop 1
	v_add_f32_dpp v121, v151, v151 quad_perm:[1,0,3,2] row_mask:0xf bank_mask:0xf
	ds_read2st64_b32 v[150:151], v143 offset0:122 offset1:123
	ds_read2st64_b32 v[152:153], v143 offset0:124 offset1:125
	ds_read2st64_b32 v[154:155], v143 offset0:126 offset1:127
	v_fmac_f32_e32 v148, v116, v116
	s_waitcnt lgkmcnt(4)
	v_sub_f32_e32 v124, v124, v147
	s_waitcnt lgkmcnt(4)
	s_nop 1
	v_add_f32_dpp v145, v121, v121 quad_perm:[2,3,0,1] row_mask:0xf bank_mask:0xf
	v_sub_f32_e32 v121, v125, v146
	v_fmac_f32_e32 v144, v98, v98
	s_waitcnt lgkmcnt(1)
	s_nop 1
	v_add_f32_dpp v147, v148, v148 quad_perm:[1,0,3,2] row_mask:0xf bank_mask:0xf
	s_waitcnt lgkmcnt(1)
	s_nop 1
	v_add_f32_dpp v125, v145, v145 row_half_mirror row_mask:0xf bank_mask:0xf
	v_fmac_f32_e32 v144, v115, v115
	v_sub_f32_e32 v122, v122, v150
	v_mul_f32_e32 v131, v20, v20
	v_fmac_f32_e32 v131, v5, v5
	s_waitcnt lgkmcnt(0)
	s_nop 1
	v_add_f32_dpp v143, v125, v125 row_mirror row_mask:0xf bank_mask:0xf
	v_sub_f32_e32 v125, v123, v151
	v_sub_f32_e32 v123, v129, v152
	v_sub_f32_e32 v35, v158, v35
	s_waitcnt lgkmcnt(1)
	v_mov_b32_e32 v129, v143
	v_mov_b32_e32 v145, v143
	s_nop 1
	v_permlane16_swap_b32_e32 v129, v145
	v_add_f32_e32 v129, v129, v145
	v_fmamk_f32 v129, v129, 0x3b800000, v244
	v_mul_f32_e32 v143, 0x4f800000, v129
	v_cmp_gt_f32_e32 vcc, s24, v129
	s_waitcnt lgkmcnt(0)
	s_nop 1
	v_add_f32_dpp v144, v144, v144 quad_perm:[1,0,3,2] row_mask:0xf bank_mask:0xf
	v_cndmask_b32_e32 v129, v129, v143, vcc
	v_sqrt_f32_e32 v143, v129
	v_fmac_f32_e32 v131, v35, v35
	v_fmac_f32_e32 v131, v52, v52
	s_waitcnt lgkmcnt(0)
	s_nop 1
	v_add_f32_dpp v144, v144, v144 quad_perm:[2,3,0,1] row_mask:0xf bank_mask:0xf
	v_add_u32_e32 v145, -1, v143
	v_fma_f32 v146, -v145, v143, v129
	v_cmp_ge_f32_e64 s[0:1], 0, v146
	v_add_u32_e32 v146, 1, v143
	v_fmac_f32_e32 v131, v67, v67
	v_cndmask_b32_e64 v145, v143, v145, s[0:1]
	v_fma_f32 v143, -v146, v143, v129
	v_cmp_lt_f32_e64 s[0:1], 0, v143
	v_fmac_f32_e32 v131, v84, v84
	v_fmac_f32_e32 v131, v99, v99
	v_cndmask_b32_e64 v143, v145, v146, s[0:1]
	v_mul_f32_e32 v145, 0x37800000, v143
	v_cndmask_b32_e32 v143, v143, v145, vcc
	s_nop 1
	v_add_f32_dpp v145, v147, v147 quad_perm:[2,3,0,1] row_mask:0xf bank_mask:0xf
	v_cmp_class_f32_e32 vcc, v129, v245
	v_fmac_f32_e32 v131, v114, v114
	v_cndmask_b32_e32 v129, v143, v129, vcc
	s_waitcnt lgkmcnt(1)
	s_nop 1
	v_add_f32_dpp v145, v145, v145 row_half_mirror row_mask:0xf bank_mask:0xf
	v_div_scale_f32 v143, s[0:1], v129, v129, s25
	v_rcp_f32_e32 v147, v143
	s_waitcnt lgkmcnt(1)
	s_nop 1
	v_add_f32_dpp v131, v131, v131 quad_perm:[1,0,3,2] row_mask:0xf bank_mask:0xf
	s_waitcnt lgkmcnt(0)
	s_nop 1
	v_add_f32_dpp v145, v145, v145 row_mirror row_mask:0xf bank_mask:0xf
	v_fma_f32 v148, -v143, v147, 1.0
	v_fmac_f32_e32 v147, v148, v147
	v_div_scale_f32 v148, vcc, s25, v129, s25
	s_waitcnt lgkmcnt(0)
	v_mov_b32_e32 v146, v145
	s_nop 1
	v_permlane16_swap_b32_e32 v145, v146
	v_add_f32_e32 v145, v145, v146
	v_fmamk_f32 v145, v145, 0x3b800000, v244
	v_mul_f32_e32 v146, 0x4f800000, v145
	v_cmp_gt_f32_e64 s[0:1], s24, v145
	v_mul_f32_e32 v149, v148, v147
	v_fma_f32 v150, -v143, v149, v148
	v_cndmask_b32_e64 v145, v145, v146, s[0:1]
	v_sqrt_f32_e32 v146, v145
	v_fmac_f32_e32 v149, v150, v147
	v_fma_f32 v143, -v143, v149, v148
	v_div_fmas_f32 v143, v143, v147, v149
	v_add_u32_e32 v148, -1, v146
	v_fma_f32 v150, -v148, v146, v145
	v_cmp_ge_f32_e64 s[2:3], 0, v150
	v_add_u32_e32 v150, 1, v146
	v_div_fixup_f32 v129, v143, v129, s25
	v_cndmask_b32_e64 v148, v146, v148, s[2:3]
	v_fma_f32 v146, -v150, v146, v145
	v_cmp_lt_f32_e64 s[2:3], 0, v146
	v_mul_f32_e32 v133, v19, v19
	v_cndmask_b32_e64 v146, v148, v150, s[2:3]
	v_mul_f32_e32 v148, 0x37800000, v146
	v_cndmask_b32_e64 v146, v146, v148, s[0:1]
	v_cmp_class_f32_e64 s[0:1], v145, v245
	s_waitcnt lgkmcnt(1)
	s_nop 1
	v_add_f32_dpp v131, v131, v131 quad_perm:[2,3,0,1] row_mask:0xf bank_mask:0xf
	v_fmac_f32_e32 v133, v4, v4
	v_cndmask_b32_e64 v145, v146, v145, s[0:1]
	s_waitcnt lgkmcnt(0)
	s_nop 1
	v_add_f32_dpp v144, v144, v144 row_half_mirror row_mask:0xf bank_mask:0xf
	v_div_scale_f32 v146, s[0:1], v145, v145, s25
	v_rcp_f32_e32 v150, v146
	v_fmac_f32_e32 v133, v36, v36
	s_waitcnt lgkmcnt(0)
	s_nop 1
	v_add_f32_dpp v144, v144, v144 row_mirror row_mask:0xf bank_mask:0xf
	v_fma_f32 v143, -v146, v150, 1.0
	v_fmac_f32_e32 v150, v143, v150
	v_div_scale_f32 v143, vcc, s25, v145, s25
	s_waitcnt lgkmcnt(0)
	v_mov_b32_e32 v147, v144
	s_nop 1
	v_permlane16_swap_b32_e32 v144, v147
	v_add_f32_e32 v144, v144, v147
	v_fmamk_f32 v144, v144, 0x3b800000, v244
	v_mul_f32_e32 v147, 0x4f800000, v144
	v_cmp_gt_f32_e64 s[0:1], s24, v144
	v_mul_f32_e32 v148, v143, v150
	v_fma_f32 v149, -v146, v148, v143
	v_cndmask_b32_e64 v144, v144, v147, s[0:1]
	v_sqrt_f32_e32 v147, v144
	v_fmac_f32_e32 v148, v149, v150
	v_fma_f32 v143, -v146, v148, v143
	v_fmac_f32_e32 v133, v51, v51
	v_add_u32_e32 v146, -1, v147
	v_fma_f32 v149, -v146, v147, v144
	v_cmp_ge_f32_e64 s[2:3], 0, v149
	v_add_u32_e32 v149, 1, v147
	v_fmac_f32_e32 v133, v68, v68
	v_cndmask_b32_e64 v146, v147, v146, s[2:3]
	v_fma_f32 v147, -v149, v147, v144
	v_cmp_lt_f32_e64 s[2:3], 0, v147
	v_fmac_f32_e32 v133, v83, v83
	v_fmac_f32_e32 v133, v100, v100
	v_cndmask_b32_e64 v146, v146, v149, s[2:3]
	v_mul_f32_e32 v147, 0x37800000, v146
	v_cndmask_b32_e64 v146, v146, v147, s[0:1]
	v_cmp_class_f32_e64 s[0:1], v144, v245
	v_fmac_f32_e32 v133, v113, v113
	v_mul_f32_e32 v135, v18, v18
	v_cndmask_b32_e64 v144, v146, v144, s[0:1]
	s_waitcnt lgkmcnt(0)
	s_nop 1
	v_add_f32_dpp v147, v131, v131 row_half_mirror row_mask:0xf bank_mask:0xf
	v_div_fmas_f32 v131, v143, v150, v148
	v_div_fixup_f32 v131, v131, v145, s25
	v_div_scale_f32 v146, s[0:1], v144, v144, s25
	s_waitcnt lgkmcnt(0)
	s_nop 1
	v_add_f32_dpp v145, v147, v147 row_mirror row_mask:0xf bank_mask:0xf
	v_rcp_f32_e32 v149, v146
	v_fmac_f32_e32 v135, v2, v2
	v_fmac_f32_e32 v135, v37, v37
	s_waitcnt lgkmcnt(1)
	v_mov_b32_e32 v147, v145
	s_nop 1
	v_permlane16_swap_b32_e32 v145, v147
	v_add_f32_e32 v145, v145, v147
	v_fmamk_f32 v145, v145, 0x3b800000, v244
	v_mul_f32_e32 v147, 0x4f800000, v145
	v_cmp_gt_f32_e64 s[0:1], s24, v145
	v_fma_f32 v143, -v146, v149, 1.0
	v_fmac_f32_e32 v149, v143, v149
	v_cndmask_b32_e64 v145, v145, v147, s[0:1]
	v_div_scale_f32 v143, vcc, s25, v144, s25
	v_sqrt_f32_e32 v147, v145
	v_mul_f32_e32 v148, v143, v149
	v_fma_f32 v150, -v146, v148, v143
	v_fmac_f32_e32 v148, v150, v149
	v_fma_f32 v143, -v146, v148, v143
	v_add_u32_e32 v146, -1, v147
	s_waitcnt lgkmcnt(0)
	s_nop 1
	v_add_f32_dpp v133, v133, v133 quad_perm:[1,0,3,2] row_mask:0xf bank_mask:0xf
	v_fma_f32 v150, -v146, v147, v145
	v_cmp_ge_f32_e64 s[2:3], 0, v150
	v_add_u32_e32 v150, 1, v147
	v_fmac_f32_e32 v135, v50, v50
	v_cndmask_b32_e64 v146, v147, v146, s[2:3]
	v_fma_f32 v147, -v150, v147, v145
	v_cmp_lt_f32_e64 s[2:3], 0, v147
	s_waitcnt lgkmcnt(0)
	s_nop 1
	v_add_f32_dpp v133, v133, v133 quad_perm:[2,3,0,1] row_mask:0xf bank_mask:0xf
	v_fmac_f32_e32 v135, v69, v69
	v_cndmask_b32_e64 v146, v146, v150, s[2:3]
	v_mul_f32_e32 v147, 0x37800000, v146
	v_cndmask_b32_e64 v146, v146, v147, s[0:1]
	v_cmp_class_f32_e64 s[0:1], v145, v245
	v_fmac_f32_e32 v135, v82, v82
	v_fmac_f32_e32 v135, v101, v101
	v_cndmask_b32_e64 v145, v146, v145, s[0:1]
	s_waitcnt lgkmcnt(0)
	s_nop 1
	v_add_f32_dpp v147, v133, v133 row_half_mirror row_mask:0xf bank_mask:0xf
	v_div_fmas_f32 v133, v143, v149, v148
	v_div_fixup_f32 v133, v133, v144, s25
	v_div_scale_f32 v146, s[0:1], v145, v145, s25
	s_waitcnt lgkmcnt(0)
	s_nop 1
	v_add_f32_dpp v144, v147, v147 row_mirror row_mask:0xf bank_mask:0xf
	v_rcp_f32_e32 v150, v146
	v_fmac_f32_e32 v135, v119, v119
	v_mul_f32_e32 v137, v16, v16
	s_waitcnt lgkmcnt(1)
	v_mov_b32_e32 v147, v144
	s_nop 1
	v_permlane16_swap_b32_e32 v144, v147
	v_add_f32_e32 v144, v144, v147
	v_fmamk_f32 v144, v144, 0x3b800000, v244
	v_mul_f32_e32 v147, 0x4f800000, v144
	v_cmp_gt_f32_e64 s[0:1], s24, v144
	v_fma_f32 v143, -v146, v150, 1.0
	v_fmac_f32_e32 v150, v143, v150
	v_cndmask_b32_e64 v144, v144, v147, s[0:1]
	v_div_scale_f32 v143, vcc, s25, v145, s25
	v_sqrt_f32_e32 v147, v144
	v_mul_f32_e32 v148, v143, v150
	v_fma_f32 v149, -v146, v148, v143
	v_fmac_f32_e32 v148, v149, v150
	v_fma_f32 v143, -v146, v148, v143
	v_add_u32_e32 v146, -1, v147
	s_waitcnt lgkmcnt(0)
	s_nop 1
	v_add_f32_dpp v135, v135, v135 quad_perm:[1,0,3,2] row_mask:0xf bank_mask:0xf
	v_fma_f32 v149, -v146, v147, v144
	v_cmp_ge_f32_e64 s[2:3], 0, v149
	v_add_u32_e32 v149, 1, v147
	v_fmac_f32_e32 v137, v0, v0
	v_cndmask_b32_e64 v146, v147, v146, s[2:3]
	v_fma_f32 v147, -v149, v147, v144
	v_cmp_lt_f32_e64 s[2:3], 0, v147
	s_waitcnt lgkmcnt(0)
	s_nop 1
	v_add_f32_dpp v135, v135, v135 quad_perm:[2,3,0,1] row_mask:0xf bank_mask:0xf
	v_fmac_f32_e32 v137, v38, v38
	v_cndmask_b32_e64 v146, v146, v149, s[2:3]
	v_mul_f32_e32 v147, 0x37800000, v146
	v_cndmask_b32_e64 v146, v146, v147, s[0:1]
	v_cmp_class_f32_e64 s[0:1], v144, v245
	v_fmac_f32_e32 v137, v48, v48
	v_fmac_f32_e32 v137, v70, v70
	v_cndmask_b32_e64 v144, v146, v144, s[0:1]
	s_waitcnt lgkmcnt(0)
	s_nop 1
	v_add_f32_dpp v147, v135, v135 row_half_mirror row_mask:0xf bank_mask:0xf
	v_div_fmas_f32 v135, v143, v150, v148
	v_div_fixup_f32 v135, v135, v145, s25
	v_div_scale_f32 v146, s[0:1], v144, v144, s25
	s_waitcnt lgkmcnt(0)
	s_nop 1
	v_add_f32_dpp v145, v147, v147 row_mirror row_mask:0xf bank_mask:0xf
	v_rcp_f32_e32 v149, v146
	v_fmac_f32_e32 v137, v80, v80
	v_fmac_f32_e32 v137, v102, v102
	v_sub_f32_e32 v118, v118, v156
	s_waitcnt lgkmcnt(0)
	v_mov_b32_e32 v147, v145
	s_nop 1
	v_permlane16_swap_b32_e32 v145, v147
	v_add_f32_e32 v145, v145, v147
	v_fmamk_f32 v145, v145, 0x3b800000, v244
	v_fmac_f32_e32 v137, v118, v118
	v_mul_f32_e32 v147, 0x4f800000, v145
	v_cmp_gt_f32_e64 s[0:1], s24, v145
	v_fma_f32 v143, -v146, v149, 1.0
	v_cndmask_b32_e64 v145, v145, v147, s[0:1]
	v_fmac_f32_e32 v149, v143, v149
	v_div_scale_f32 v143, vcc, s25, v144, s25
	v_sqrt_f32_e32 v147, v145
	v_mul_f32_e32 v148, v143, v149
	v_fma_f32 v150, -v146, v148, v143
	v_fmac_f32_e32 v148, v150, v149
	v_fma_f32 v143, -v146, v148, v143
	v_add_u32_e32 v146, -1, v147
	s_waitcnt lgkmcnt(0)
	s_nop 1
	v_add_f32_dpp v137, v137, v137 quad_perm:[1,0,3,2] row_mask:0xf bank_mask:0xf
	v_fma_f32 v150, -v146, v147, v145
	v_cmp_ge_f32_e64 s[2:3], 0, v150
	v_add_u32_e32 v150, 1, v147
	v_mul_f32_e32 v139, v17, v17
	v_cndmask_b32_e64 v146, v147, v146, s[2:3]
	v_fma_f32 v147, -v150, v147, v145
	v_cmp_lt_f32_e64 s[2:3], 0, v147
	s_waitcnt lgkmcnt(0)
	s_nop 1
	v_add_f32_dpp v137, v137, v137 quad_perm:[2,3,0,1] row_mask:0xf bank_mask:0xf
	v_fmac_f32_e32 v139, v3, v3
	v_cndmask_b32_e64 v146, v146, v150, s[2:3]
	v_mul_f32_e32 v147, 0x37800000, v146
	v_cndmask_b32_e64 v146, v146, v147, s[0:1]
	v_cmp_class_f32_e64 s[0:1], v145, v245
	v_fmac_f32_e32 v139, v39, v39
	v_fmac_f32_e32 v139, v49, v49
	v_cndmask_b32_e64 v145, v146, v145, s[0:1]
	s_waitcnt lgkmcnt(0)
	s_nop 1
	v_add_f32_dpp v147, v137, v137 row_half_mirror row_mask:0xf bank_mask:0xf
	v_div_fmas_f32 v137, v143, v149, v148
	v_div_fixup_f32 v137, v137, v144, s25
	v_div_scale_f32 v146, s[0:1], v145, v145, s25
	s_waitcnt lgkmcnt(0)
	s_nop 1
	v_add_f32_dpp v144, v147, v147 row_mirror row_mask:0xf bank_mask:0xf
	v_fmac_f32_e32 v139, v71, v71
	v_rcp_f32_e32 v150, v146
	v_fmac_f32_e32 v139, v81, v81
	v_fmac_f32_e32 v139, v103, v103
	s_waitcnt lgkmcnt(0)
	v_mov_b32_e32 v147, v144
	s_nop 1
	v_permlane16_swap_b32_e32 v144, v147
	v_add_f32_e32 v144, v144, v147
	v_sub_f32_e32 v120, v120, v157
	v_fmamk_f32 v144, v144, 0x3b800000, v244
	v_fmac_f32_e32 v139, v120, v120
	v_mul_f32_e32 v147, 0x4f800000, v144
	v_cmp_gt_f32_e64 s[0:1], s24, v144
	v_fma_f32 v143, -v146, v150, 1.0
	v_cndmask_b32_e64 v144, v144, v147, s[0:1]
	v_fmac_f32_e32 v150, v143, v150
	v_div_scale_f32 v143, vcc, s25, v145, s25
	v_sqrt_f32_e32 v147, v144
	v_mul_f32_e32 v148, v143, v150
	v_fma_f32 v149, -v146, v148, v143
	v_fmac_f32_e32 v148, v149, v150
	v_fma_f32 v143, -v146, v148, v143
	v_add_u32_e32 v146, -1, v147
	s_waitcnt lgkmcnt(0)
	s_nop 1
	v_add_f32_dpp v139, v139, v139 quad_perm:[1,0,3,2] row_mask:0xf bank_mask:0xf
	v_fma_f32 v149, -v146, v147, v144
	v_cmp_ge_f32_e64 s[2:3], 0, v149
	v_add_u32_e32 v149, 1, v147
	v_mul_f32_e32 v141, v31, v31
	v_cndmask_b32_e64 v146, v147, v146, s[2:3]
	v_fma_f32 v147, -v149, v147, v144
	v_cmp_lt_f32_e64 s[2:3], 0, v147
	s_waitcnt lgkmcnt(0)
	s_nop 1
	v_add_f32_dpp v139, v139, v139 quad_perm:[2,3,0,1] row_mask:0xf bank_mask:0xf
	v_fmac_f32_e32 v141, v15, v15
	v_cndmask_b32_e64 v146, v146, v149, s[2:3]
	v_mul_f32_e32 v147, 0x37800000, v146
	v_cndmask_b32_e64 v146, v146, v147, s[0:1]
	v_cmp_class_f32_e64 s[0:1], v144, v245
	v_fmac_f32_e32 v141, v40, v40
	v_fmac_f32_e32 v141, v63, v63
	v_cndmask_b32_e64 v144, v146, v144, s[0:1]
	s_waitcnt lgkmcnt(0)
	s_nop 1
	v_add_f32_dpp v147, v139, v139 row_half_mirror row_mask:0xf bank_mask:0xf
	v_div_fmas_f32 v139, v143, v150, v148
	v_div_fixup_f32 v139, v139, v145, s25
	v_div_scale_f32 v146, s[0:1], v144, v144, s25
	s_waitcnt lgkmcnt(0)
	s_nop 1
	v_add_f32_dpp v145, v147, v147 row_mirror row_mask:0xf bank_mask:0xf
	v_fmac_f32_e32 v141, v72, v72
	v_rcp_f32_e32 v149, v146
	v_fmac_f32_e32 v141, v95, v95
	v_fmac_f32_e32 v141, v104, v104
	s_waitcnt lgkmcnt(0)
	v_mov_b32_e32 v147, v145
	s_nop 1
	v_permlane16_swap_b32_e32 v145, v147
	v_add_f32_e32 v145, v145, v147
	v_fmamk_f32 v145, v145, 0x3b800000, v244
	v_fmac_f32_e32 v141, v121, v121
	v_mul_f32_e32 v147, 0x4f800000, v145
	v_cmp_gt_f32_e64 s[0:1], s24, v145
	v_fma_f32 v143, -v146, v149, 1.0
	v_cndmask_b32_e64 v145, v145, v147, s[0:1]
	v_fmac_f32_e32 v149, v143, v149
	v_div_scale_f32 v143, vcc, s25, v144, s25
	v_sqrt_f32_e32 v147, v145
	v_mul_f32_e32 v148, v143, v149
	v_fma_f32 v150, -v146, v148, v143
	v_fmac_f32_e32 v148, v150, v149
	v_fma_f32 v143, -v146, v148, v143
	v_add_u32_e32 v146, -1, v147
	s_waitcnt lgkmcnt(0)
	s_nop 1
	v_add_f32_dpp v141, v141, v141 quad_perm:[1,0,3,2] row_mask:0xf bank_mask:0xf
	v_fma_f32 v150, -v146, v147, v145
	v_cmp_ge_f32_e64 s[2:3], 0, v150
	v_add_u32_e32 v150, 1, v147
	v_mul_f32_e32 v142, v30, v30
	v_cndmask_b32_e64 v146, v147, v146, s[2:3]
	v_fma_f32 v147, -v150, v147, v145
	v_cmp_lt_f32_e64 s[2:3], 0, v147
	s_waitcnt lgkmcnt(0)
	s_nop 1
	v_add_f32_dpp v141, v141, v141 quad_perm:[2,3,0,1] row_mask:0xf bank_mask:0xf
	v_fmac_f32_e32 v142, v14, v14
	v_cndmask_b32_e64 v146, v146, v150, s[2:3]
	v_mul_f32_e32 v147, 0x37800000, v146
	v_cndmask_b32_e64 v146, v146, v147, s[0:1]
	v_cmp_class_f32_e64 s[0:1], v145, v245
	v_fmac_f32_e32 v142, v41, v41
	v_fmac_f32_e32 v142, v62, v62
	v_cndmask_b32_e64 v145, v146, v145, s[0:1]
	s_waitcnt lgkmcnt(0)
	s_nop 1
	v_add_f32_dpp v147, v141, v141 row_half_mirror row_mask:0xf bank_mask:0xf
	v_div_fmas_f32 v141, v143, v149, v148
	v_div_fixup_f32 v141, v141, v144, s25
	v_div_scale_f32 v146, s[0:1], v145, v145, s25
	s_waitcnt lgkmcnt(0)
	s_nop 1
	v_add_f32_dpp v144, v147, v147 row_mirror row_mask:0xf bank_mask:0xf
	v_fmac_f32_e32 v142, v73, v73
	v_rcp_f32_e32 v150, v146
	v_fmac_f32_e32 v142, v94, v94
	v_fmac_f32_e32 v142, v105, v105
	s_waitcnt lgkmcnt(0)
	v_mov_b32_e32 v147, v144
	s_nop 1
	v_permlane16_swap_b32_e32 v144, v147
	v_add_f32_e32 v144, v144, v147
	v_fmamk_f32 v144, v144, 0x3b800000, v244
	v_fmac_f32_e32 v142, v124, v124
	v_mul_f32_e32 v147, 0x4f800000, v144
	v_cmp_gt_f32_e64 s[0:1], s24, v144
	v_fma_f32 v143, -v146, v150, 1.0
	v_cndmask_b32_e64 v144, v144, v147, s[0:1]
	v_fmac_f32_e32 v150, v143, v150
	v_div_scale_f32 v143, vcc, s25, v145, s25
	v_sqrt_f32_e32 v147, v144
	v_mul_f32_e32 v148, v143, v150
	v_fma_f32 v149, -v146, v148, v143
	v_fmac_f32_e32 v148, v149, v150
	v_fma_f32 v143, -v146, v148, v143
	v_add_u32_e32 v146, -1, v147
	s_waitcnt lgkmcnt(0)
	s_nop 1
	v_add_f32_dpp v142, v142, v142 quad_perm:[1,0,3,2] row_mask:0xf bank_mask:0xf
	v_fma_f32 v149, -v146, v147, v144
	v_cmp_ge_f32_e64 s[2:3], 0, v149
	v_add_u32_e32 v149, 1, v147
	v_mul_f32_e32 v140, v29, v29
	v_cndmask_b32_e64 v146, v147, v146, s[2:3]
	v_fma_f32 v147, -v149, v147, v144
	v_cmp_lt_f32_e64 s[2:3], 0, v147
	s_waitcnt lgkmcnt(0)
	s_nop 1
	v_add_f32_dpp v142, v142, v142 quad_perm:[2,3,0,1] row_mask:0xf bank_mask:0xf
	v_fmac_f32_e32 v140, v13, v13
	v_cndmask_b32_e64 v146, v146, v149, s[2:3]
	v_mul_f32_e32 v147, 0x37800000, v146
	v_cndmask_b32_e64 v146, v146, v147, s[0:1]
	v_cmp_class_f32_e64 s[0:1], v144, v245
	v_fmac_f32_e32 v140, v42, v42
	v_fmac_f32_e32 v140, v61, v61
	v_cndmask_b32_e64 v144, v146, v144, s[0:1]
	s_waitcnt lgkmcnt(0)
	s_nop 1
	v_add_f32_dpp v147, v142, v142 row_half_mirror row_mask:0xf bank_mask:0xf
	v_div_fmas_f32 v142, v143, v150, v148
	v_div_fixup_f32 v142, v142, v145, s25
	v_div_scale_f32 v146, s[0:1], v144, v144, s25
	s_waitcnt lgkmcnt(0)
	s_nop 1
	v_add_f32_dpp v145, v147, v147 row_mirror row_mask:0xf bank_mask:0xf
	v_fmac_f32_e32 v140, v74, v74
	v_rcp_f32_e32 v149, v146
	v_fmac_f32_e32 v140, v93, v93
	v_fmac_f32_e32 v140, v106, v106
	s_waitcnt lgkmcnt(0)
	v_mov_b32_e32 v147, v145
	s_nop 1
	v_permlane16_swap_b32_e32 v145, v147
	v_add_f32_e32 v145, v145, v147
	v_fmamk_f32 v145, v145, 0x3b800000, v244
	v_fmac_f32_e32 v140, v122, v122
	v_mul_f32_e32 v147, 0x4f800000, v145
	v_cmp_gt_f32_e64 s[0:1], s24, v145
	v_fma_f32 v143, -v146, v149, 1.0
	v_cndmask_b32_e64 v145, v145, v147, s[0:1]
	v_fmac_f32_e32 v149, v143, v149
	v_div_scale_f32 v143, vcc, s25, v144, s25
	v_sqrt_f32_e32 v147, v145
	v_mul_f32_e32 v148, v143, v149
	v_fma_f32 v150, -v146, v148, v143
	v_fmac_f32_e32 v148, v150, v149
	v_fma_f32 v143, -v146, v148, v143
	v_add_u32_e32 v146, -1, v147
	s_waitcnt lgkmcnt(0)
	s_nop 1
	v_add_f32_dpp v140, v140, v140 quad_perm:[1,0,3,2] row_mask:0xf bank_mask:0xf
	v_fma_f32 v150, -v146, v147, v145
	v_cmp_ge_f32_e64 s[2:3], 0, v150
	v_add_u32_e32 v150, 1, v147
	v_mul_f32_e32 v138, v28, v28
	v_cndmask_b32_e64 v146, v147, v146, s[2:3]
	v_fma_f32 v147, -v150, v147, v145
	v_cmp_lt_f32_e64 s[2:3], 0, v147
	s_waitcnt lgkmcnt(0)
	s_nop 1
	v_add_f32_dpp v140, v140, v140 quad_perm:[2,3,0,1] row_mask:0xf bank_mask:0xf
	v_fmac_f32_e32 v138, v12, v12
	v_cndmask_b32_e64 v146, v146, v150, s[2:3]
	v_mul_f32_e32 v147, 0x37800000, v146
	v_cndmask_b32_e64 v146, v146, v147, s[0:1]
	v_cmp_class_f32_e64 s[0:1], v145, v245
	v_fmac_f32_e32 v138, v43, v43
	v_fmac_f32_e32 v138, v60, v60
	v_cndmask_b32_e64 v145, v146, v145, s[0:1]
	s_waitcnt lgkmcnt(0)
	s_nop 1
	v_add_f32_dpp v147, v140, v140 row_half_mirror row_mask:0xf bank_mask:0xf
	v_div_fmas_f32 v140, v143, v149, v148
	v_div_fixup_f32 v140, v140, v144, s25
	v_div_scale_f32 v146, s[0:1], v145, v145, s25
	s_waitcnt lgkmcnt(0)
	s_nop 1
	v_add_f32_dpp v144, v147, v147 row_mirror row_mask:0xf bank_mask:0xf
	v_fmac_f32_e32 v138, v75, v75
	v_rcp_f32_e32 v150, v146
	v_fmac_f32_e32 v138, v92, v92
	v_fmac_f32_e32 v138, v107, v107
	s_waitcnt lgkmcnt(0)
	v_mov_b32_e32 v147, v144
	s_nop 1
	v_permlane16_swap_b32_e32 v144, v147
	v_add_f32_e32 v144, v144, v147
	v_fmamk_f32 v144, v144, 0x3b800000, v244
	v_fmac_f32_e32 v138, v125, v125
	v_mul_f32_e32 v147, 0x4f800000, v144
	v_cmp_gt_f32_e64 s[0:1], s24, v144
	v_fma_f32 v143, -v146, v150, 1.0
	v_cndmask_b32_e64 v144, v144, v147, s[0:1]
	v_fmac_f32_e32 v150, v143, v150
	v_div_scale_f32 v143, vcc, s25, v145, s25
	v_sqrt_f32_e32 v147, v144
	v_mul_f32_e32 v148, v143, v150
	v_fma_f32 v149, -v146, v148, v143
	v_fmac_f32_e32 v148, v149, v150
	v_fma_f32 v143, -v146, v148, v143
	v_add_u32_e32 v146, -1, v147
	s_waitcnt lgkmcnt(0)
	s_nop 1
	v_add_f32_dpp v138, v138, v138 quad_perm:[1,0,3,2] row_mask:0xf bank_mask:0xf
	v_fma_f32 v149, -v146, v147, v144
	v_cmp_ge_f32_e64 s[2:3], 0, v149
	v_add_u32_e32 v149, 1, v147
	v_mul_f32_e32 v136, v27, v27
	v_cndmask_b32_e64 v146, v147, v146, s[2:3]
	v_fma_f32 v147, -v149, v147, v144
	v_cmp_lt_f32_e64 s[2:3], 0, v147
	s_waitcnt lgkmcnt(0)
	s_nop 1
	v_add_f32_dpp v138, v138, v138 quad_perm:[2,3,0,1] row_mask:0xf bank_mask:0xf
	v_fmac_f32_e32 v136, v11, v11
	v_cndmask_b32_e64 v146, v146, v149, s[2:3]
	v_mul_f32_e32 v147, 0x37800000, v146
	v_cndmask_b32_e64 v146, v146, v147, s[0:1]
	v_cmp_class_f32_e64 s[0:1], v144, v245
	v_fmac_f32_e32 v136, v44, v44
	v_fmac_f32_e32 v136, v59, v59
	v_cndmask_b32_e64 v144, v146, v144, s[0:1]
	s_waitcnt lgkmcnt(0)
	s_nop 1
	v_add_f32_dpp v147, v138, v138 row_half_mirror row_mask:0xf bank_mask:0xf
	v_div_fmas_f32 v138, v143, v150, v148
	v_div_fixup_f32 v138, v138, v145, s25
	v_div_scale_f32 v146, s[0:1], v144, v144, s25
	s_waitcnt lgkmcnt(0)
	s_nop 1
	v_add_f32_dpp v145, v147, v147 row_mirror row_mask:0xf bank_mask:0xf
	v_fmac_f32_e32 v136, v76, v76
	v_rcp_f32_e32 v149, v146
	v_fmac_f32_e32 v136, v91, v91
	v_fmac_f32_e32 v136, v108, v108
	s_waitcnt lgkmcnt(0)
	v_mov_b32_e32 v147, v145
	s_nop 1
	v_permlane16_swap_b32_e32 v145, v147
	v_add_f32_e32 v145, v145, v147
	v_fmamk_f32 v145, v145, 0x3b800000, v244
	v_fmac_f32_e32 v136, v123, v123
	v_mul_f32_e32 v147, 0x4f800000, v145
	v_cmp_gt_f32_e64 s[0:1], s24, v145
	v_fma_f32 v143, -v146, v149, 1.0
	v_cndmask_b32_e64 v145, v145, v147, s[0:1]
	v_fmac_f32_e32 v149, v143, v149
	v_div_scale_f32 v143, vcc, s25, v144, s25
	v_sqrt_f32_e32 v147, v145
	v_mul_f32_e32 v148, v143, v149
	v_fma_f32 v150, -v146, v148, v143
	v_fmac_f32_e32 v148, v150, v149
	v_fma_f32 v143, -v146, v148, v143
	v_add_u32_e32 v146, -1, v147
	s_waitcnt lgkmcnt(0)
	s_nop 1
	v_add_f32_dpp v136, v136, v136 quad_perm:[1,0,3,2] row_mask:0xf bank_mask:0xf
	v_fma_f32 v150, -v146, v147, v145
	v_cmp_ge_f32_e64 s[2:3], 0, v150
	v_add_u32_e32 v150, 1, v147
	v_mul_f32_e32 v134, v26, v26
	v_cndmask_b32_e64 v146, v147, v146, s[2:3]
	v_fma_f32 v147, -v150, v147, v145
	v_cmp_lt_f32_e64 s[2:3], 0, v147
	s_waitcnt lgkmcnt(0)
	s_nop 1
	v_add_f32_dpp v136, v136, v136 quad_perm:[2,3,0,1] row_mask:0xf bank_mask:0xf
	v_fmac_f32_e32 v134, v8, v8
	v_cndmask_b32_e64 v146, v146, v150, s[2:3]
	v_mul_f32_e32 v147, 0x37800000, v146
	v_cndmask_b32_e64 v146, v146, v147, s[0:1]
	v_cmp_class_f32_e64 s[0:1], v145, v245
	v_fmac_f32_e32 v134, v45, v45
	v_fmac_f32_e32 v134, v58, v58
	v_cndmask_b32_e64 v145, v146, v145, s[0:1]
	s_waitcnt lgkmcnt(0)
	s_nop 1
	v_add_f32_dpp v147, v136, v136 row_half_mirror row_mask:0xf bank_mask:0xf
	v_div_fmas_f32 v136, v143, v149, v148
	v_div_fixup_f32 v136, v136, v144, s25
	v_div_scale_f32 v146, s[0:1], v145, v145, s25
	s_waitcnt lgkmcnt(0)
	s_nop 1
	v_add_f32_dpp v144, v147, v147 row_mirror row_mask:0xf bank_mask:0xf
	v_fmac_f32_e32 v134, v77, v77
	v_rcp_f32_e32 v150, v146
	v_fmac_f32_e32 v134, v90, v90
	v_fmac_f32_e32 v134, v109, v109
	s_waitcnt lgkmcnt(0)
	v_mov_b32_e32 v147, v144
	s_nop 1
	v_permlane16_swap_b32_e32 v144, v147
	v_add_f32_e32 v144, v144, v147
	v_sub_f32_e32 v127, v127, v153
	v_fmamk_f32 v144, v144, 0x3b800000, v244
	v_fmac_f32_e32 v134, v127, v127
	v_mul_f32_e32 v147, 0x4f800000, v144
	v_cmp_gt_f32_e64 s[0:1], s24, v144
	v_fma_f32 v143, -v146, v150, 1.0
	v_cndmask_b32_e64 v144, v144, v147, s[0:1]
	v_fmac_f32_e32 v150, v143, v150
	v_div_scale_f32 v143, vcc, s25, v145, s25
	v_sqrt_f32_e32 v147, v144
	v_mul_f32_e32 v148, v143, v150
	v_fma_f32 v149, -v146, v148, v143
	v_fmac_f32_e32 v148, v149, v150
	v_fma_f32 v143, -v146, v148, v143
	v_add_u32_e32 v146, -1, v147
	s_waitcnt lgkmcnt(0)
	s_nop 1
	v_add_f32_dpp v134, v134, v134 quad_perm:[1,0,3,2] row_mask:0xf bank_mask:0xf
	v_fma_f32 v149, -v146, v147, v144
	v_cmp_ge_f32_e64 s[2:3], 0, v149
	v_add_u32_e32 v149, 1, v147
	v_mul_f32_e32 v132, v24, v24
	v_cndmask_b32_e64 v146, v147, v146, s[2:3]
	v_fma_f32 v147, -v149, v147, v144
	v_cmp_lt_f32_e64 s[2:3], 0, v147
	s_waitcnt lgkmcnt(0)
	s_nop 1
	v_add_f32_dpp v134, v134, v134 quad_perm:[2,3,0,1] row_mask:0xf bank_mask:0xf
	v_fmac_f32_e32 v132, v6, v6
	v_cndmask_b32_e64 v146, v146, v149, s[2:3]
	v_mul_f32_e32 v147, 0x37800000, v146
	v_cndmask_b32_e64 v146, v146, v147, s[0:1]
	v_cmp_class_f32_e64 s[0:1], v144, v245
	v_fmac_f32_e32 v132, v46, v46
	v_fmac_f32_e32 v132, v56, v56
	v_cndmask_b32_e64 v144, v146, v144, s[0:1]
	s_waitcnt lgkmcnt(0)
	s_nop 1
	v_add_f32_dpp v147, v134, v134 row_half_mirror row_mask:0xf bank_mask:0xf
	v_div_fmas_f32 v134, v143, v150, v148
	v_div_fixup_f32 v134, v134, v145, s25
	v_div_scale_f32 v146, s[0:1], v144, v144, s25
	s_waitcnt lgkmcnt(0)
	s_nop 1
	v_add_f32_dpp v145, v147, v147 row_mirror row_mask:0xf bank_mask:0xf
	v_fmac_f32_e32 v132, v78, v78
	v_rcp_f32_e32 v149, v146
	v_fmac_f32_e32 v132, v88, v88
	v_fmac_f32_e32 v132, v110, v110
	s_waitcnt lgkmcnt(0)
	v_mov_b32_e32 v147, v145
	s_nop 1
	v_permlane16_swap_b32_e32 v145, v147
	v_add_f32_e32 v145, v145, v147
	v_sub_f32_e32 v126, v126, v154
	v_fmamk_f32 v145, v145, 0x3b800000, v244
	v_fmac_f32_e32 v132, v126, v126
	v_mul_f32_e32 v147, 0x4f800000, v145
	v_cmp_gt_f32_e64 s[0:1], s24, v145
	v_fma_f32 v143, -v146, v149, 1.0
	v_cndmask_b32_e64 v145, v145, v147, s[0:1]
	v_fmac_f32_e32 v149, v143, v149
	v_div_scale_f32 v143, vcc, s25, v144, s25
	v_sqrt_f32_e32 v147, v145
	v_mul_f32_e32 v148, v143, v149
	v_fma_f32 v150, -v146, v148, v143
	v_fmac_f32_e32 v148, v150, v149
	v_fma_f32 v143, -v146, v148, v143
	v_add_u32_e32 v146, -1, v147
	s_waitcnt lgkmcnt(0)
	s_nop 1
	v_add_f32_dpp v132, v132, v132 quad_perm:[1,0,3,2] row_mask:0xf bank_mask:0xf
	v_fma_f32 v150, -v146, v147, v145
	v_cmp_ge_f32_e64 s[2:3], 0, v150
	v_add_u32_e32 v150, 1, v147
	v_mul_f32_e32 v130, v25, v25
	v_cndmask_b32_e64 v146, v147, v146, s[2:3]
	v_fma_f32 v147, -v150, v147, v145
	v_cmp_lt_f32_e64 s[2:3], 0, v147
	s_waitcnt lgkmcnt(0)
	s_nop 1
	v_add_f32_dpp v132, v132, v132 quad_perm:[2,3,0,1] row_mask:0xf bank_mask:0xf
	v_fmac_f32_e32 v130, v9, v9
	v_cndmask_b32_e64 v146, v146, v150, s[2:3]
	v_mul_f32_e32 v147, 0x37800000, v146
	v_cndmask_b32_e64 v146, v146, v147, s[0:1]
	v_cmp_class_f32_e64 s[0:1], v145, v245
	v_fmac_f32_e32 v130, v47, v47
	v_fmac_f32_e32 v130, v57, v57
	v_cndmask_b32_e64 v145, v146, v145, s[0:1]
	v_div_scale_f32 v146, s[0:1], v145, v145, s25
	s_waitcnt lgkmcnt(0)
	s_nop 1
	v_add_f32_dpp v147, v132, v132 row_half_mirror row_mask:0xf bank_mask:0xf
	v_rcp_f32_e32 v150, v146
	v_div_fmas_f32 v132, v143, v149, v148
	v_div_fixup_f32 v132, v132, v144, s25
	v_fma_f32 v143, -v146, v150, 1.0
	v_fmac_f32_e32 v150, v143, v150
	s_waitcnt lgkmcnt(0)
	s_nop 1
	v_add_f32_dpp v143, v147, v147 row_mirror row_mask:0xf bank_mask:0xf
	v_fmac_f32_e32 v130, v79, v79
	v_fmac_f32_e32 v130, v89, v89
	v_fmac_f32_e32 v130, v111, v111
	v_sub_f32_e32 v128, v128, v155
	s_waitcnt lgkmcnt(0)
	v_mov_b32_e32 v144, v143
	s_nop 1
	v_permlane16_swap_b32_e32 v143, v144
	v_add_f32_e32 v143, v143, v144
	v_fmamk_f32 v143, v143, 0x3b800000, v244
	v_fmac_f32_e32 v130, v128, v128
	v_mul_f32_e32 v144, 0x4f800000, v143
	v_cmp_gt_f32_e64 s[0:1], s24, v143
	v_div_scale_f32 v147, vcc, s25, v145, s25
	v_cndmask_b32_e64 v143, v143, v144, s[0:1]
	v_sqrt_f32_e32 v144, v143
	v_mul_f32_e32 v148, v147, v150
	v_fma_f32 v149, -v146, v148, v147
	v_fmac_f32_e32 v148, v149, v150
	v_fma_f32 v146, -v146, v148, v147
	v_add_u32_e32 v147, -1, v144
	s_waitcnt lgkmcnt(0)
	s_nop 1
	v_add_f32_dpp v130, v130, v130 quad_perm:[1,0,3,2] row_mask:0xf bank_mask:0xf
	v_fma_f32 v151, -v147, v144, v143
	v_cmp_ge_f32_e64 s[2:3], 0, v151
	v_add_u32_e32 v151, 1, v144
	global_load_dword v149, v[196:197], off offset:1024
	v_cndmask_b32_e64 v147, v144, v147, s[2:3]
	v_fma_f32 v144, -v151, v144, v143
	v_cmp_lt_f32_e64 s[2:3], 0, v144
	s_waitcnt lgkmcnt(0)
	s_nop 1
	v_add_f32_dpp v130, v130, v130 quad_perm:[2,3,0,1] row_mask:0xf bank_mask:0xf
	v_mul_f32_e32 v112, v112, v129
	v_cndmask_b32_e64 v144, v147, v151, s[2:3]
	v_mul_f32_e32 v147, 0x37800000, v144
	v_cndmask_b32_e64 v144, v144, v147, s[0:1]
	v_cmp_class_f32_e64 s[0:1], v143, v245
	v_lshlrev_b32_e32 v153, 12, v222
	v_mul_f32_e32 v22, v22, v129
	v_cndmask_b32_e64 v143, v144, v143, s[0:1]
	v_div_scale_f32 v144, s[0:1], v143, v143, s25
	s_waitcnt lgkmcnt(0)
	s_nop 1
	v_add_f32_dpp v147, v130, v130 row_half_mirror row_mask:0xf bank_mask:0xf
	v_rcp_f32_e32 v151, v144
	v_div_fmas_f32 v130, v146, v150, v148
	v_div_fixup_f32 v130, v130, v145, s25
	v_fma_f32 v145, -v144, v151, 1.0
	global_load_dword v148, v[196:197], off offset:1152
	v_fmac_f32_e32 v151, v145, v151
	s_waitcnt lgkmcnt(0)
	s_nop 1
	v_add_f32_dpp v145, v147, v147 row_mirror row_mask:0xf bank_mask:0xf
	v_div_scale_f32 v147, vcc, s25, v143, s25
	v_mul_f32_e32 v150, v147, v151
	v_fma_f32 v152, -v144, v150, v147
	s_waitcnt lgkmcnt(0)
	v_mov_b32_e32 v146, v145
	s_nop 1
	v_permlane16_swap_b32_e32 v145, v146
	v_add_f32_e32 v145, v145, v146
	v_fmamk_f32 v145, v145, 0x3b800000, v244
	v_mul_f32_e32 v146, 0x4f800000, v145
	v_cmp_gt_f32_e64 s[0:1], s24, v145
	v_fmac_f32_e32 v150, v152, v151
	v_fma_f32 v144, -v144, v150, v147
	v_cndmask_b32_e64 v145, v145, v146, s[0:1]
	v_sqrt_f32_e32 v146, v145
	v_div_fmas_f32 v144, v144, v151, v150
	v_div_fixup_f32 v143, v144, v143, s25
	v_add3_u32 v153, s37, v194, v153
	v_add_u32_e32 v147, -1, v146
	v_fma_f32 v152, -v147, v146, v145
	v_cmp_ge_f32_e64 s[2:3], 0, v152
	v_add_u32_e32 v152, 1, v146
	v_mul_f32_e32 v10, v10, v131
	v_cndmask_b32_e64 v147, v146, v147, s[2:3]
	v_fma_f32 v146, -v152, v146, v145
	v_cmp_lt_f32_e64 s[2:3], 0, v146
	v_mul_f32_e32 v7, v7, v133
	v_mul_f32_e32 v5, v5, v135
	v_cndmask_b32_e64 v146, v147, v152, s[2:3]
	v_mul_f32_e32 v147, 0x37800000, v146
	v_cndmask_b32_e64 v146, v146, v147, s[0:1]
	v_cmp_class_f32_e64 s[0:1], v145, v245
	v_mul_f32_e32 v4, v4, v137
	v_mul_f32_e32 v2, v2, v139
	v_cndmask_b32_e64 v145, v146, v145, s[0:1]
	v_div_scale_f32 v146, s[0:1], v145, v145, s25
	v_rcp_f32_e32 v147, v146
	v_mul_f32_e32 v0, v0, v141
	v_mul_f32_e32 v3, v3, v142
	v_mul_f32_e32 v15, v15, v140
	v_fma_f32 v144, -v146, v147, 1.0
	v_fmac_f32_e32 v147, v144, v147
	v_div_scale_f32 v144, vcc, s25, v145, s25
	v_mul_f32_e32 v150, v144, v147
	v_fma_f32 v151, -v146, v150, v144
	v_fmac_f32_e32 v150, v151, v147
	v_fma_f32 v144, -v146, v150, v144
	v_div_fmas_f32 v144, v144, v147, v150
	v_div_fixup_f32 v144, v144, v145, s25
	global_load_dword v145, v[196:197], off offset:1280
	global_load_dword v146, v[196:197], off offset:1408
	global_load_dword v147, v[196:197], off offset:1536
	global_load_dword v150, v[196:197], off offset:1664
	global_load_dword v151, v[196:197], off offset:1792
	global_load_dword v152, v[196:197], off offset:1920
	v_mul_f32_e32 v14, v14, v138
	v_mul_f32_e32 v13, v13, v136
	v_mul_f32_e32 v12, v12, v134
	v_mul_f32_e32 v11, v11, v132
	v_mul_f32_e32 v8, v8, v130
	s_waitcnt vmcnt(7)
	v_mul_f32_e32 v112, v112, v149
	v_mul_f32_e32 v10, v10, v149
	v_mul_f32_e32 v7, v7, v149
	v_mul_f32_e32 v5, v5, v149
	v_mul_f32_e32 v4, v4, v149
	v_mul_f32_e32 v2, v2, v149
	v_mul_f32_e32 v0, v0, v149
	v_mul_f32_e32 v3, v3, v149
	v_mul_f32_e32 v15, v15, v149
	v_mul_f32_e32 v14, v14, v149
	v_mul_f32_e32 v13, v13, v149
	v_mul_f32_e32 v12, v12, v149
	v_mul_f32_e32 v11, v11, v149
	v_mul_f32_e32 v8, v8, v149
	v_mul_f32_e32 v6, v6, v143
	v_mul_f32_e32 v6, v149, v6
	v_mul_f32_e32 v9, v9, v144
	v_mul_f32_e32 v9, v149, v9
	s_add_i32 s0, s4, s33
	s_add_i32 s4, s0, s35
	s_lshl_b32 s0, s48, 5
	s_and_b32 s0, s0, 0xe00
	s_waitcnt vmcnt(6)
	v_mul_f32_e32 v22, v22, v148
	ds_write2_b32 v153, v112, v22 offset1:32
	v_mul_f32_e32 v22, v23, v131
	v_mul_f32_e32 v22, v22, v148
	v_add_u32_e32 v23, 0x400, v153
	ds_write2_b32 v23, v10, v22 offset1:32
	v_mul_f32_e32 v10, v21, v133
	v_mul_f32_e32 v10, v10, v148
	v_add_u32_e32 v21, 0x800, v153
	ds_write2_b32 v21, v7, v10 offset1:32
	v_mul_f32_e32 v7, v20, v135
	v_mul_f32_e32 v7, v7, v148
	v_add_u32_e32 v10, 0xc00, v153
	ds_write2_b32 v10, v5, v7 offset1:32
	v_mul_f32_e32 v5, v19, v137
	v_mul_f32_e32 v5, v5, v148
	v_add_u32_e32 v7, 0x2000, v153
	ds_write2_b32 v7, v4, v5 offset1:32
	v_mul_f32_e32 v4, v18, v139
	v_mul_f32_e32 v4, v4, v148
	v_add_u32_e32 v5, 0x2400, v153
	ds_write2_b32 v5, v2, v4 offset1:32
	v_mul_f32_e32 v2, v16, v141
	v_mul_f32_e32 v2, v2, v148
	v_add_u32_e32 v4, 0x2800, v153
	ds_write2_b32 v4, v0, v2 offset1:32
	v_mul_f32_e32 v0, v17, v142
	v_mul_f32_e32 v0, v0, v148
	v_add_u32_e32 v2, 0x2c00, v153
	ds_write2_b32 v2, v3, v0 offset1:32
	v_mul_f32_e32 v0, v31, v140
	v_mul_f32_e32 v0, v0, v148
	v_add_u32_e32 v3, 0x4000, v153
	ds_write2_b32 v3, v15, v0 offset1:32
	v_mul_f32_e32 v0, v30, v138
	v_mul_f32_e32 v0, v0, v148
	v_add_u32_e32 v15, 0x4400, v153
	ds_write2_b32 v15, v14, v0 offset1:32
	v_mul_f32_e32 v0, v29, v136
	v_mul_f32_e32 v0, v0, v148
	v_add_u32_e32 v14, 0x4800, v153
	ds_write2_b32 v14, v13, v0 offset1:32
	v_mul_f32_e32 v0, v28, v134
	v_mul_f32_e32 v0, v0, v148
	v_add_u32_e32 v13, 0x4c00, v153
	ds_write2_b32 v13, v12, v0 offset1:32
	v_mul_f32_e32 v0, v27, v132
	v_mul_f32_e32 v0, v0, v148
	v_add_u32_e32 v12, 0x6000, v153
	ds_write2_b32 v12, v11, v0 offset1:32
	v_mul_f32_e32 v0, v26, v130
	v_mul_f32_e32 v0, v0, v148
	v_add_u32_e32 v11, 0x6400, v153
	ds_write2_b32 v11, v8, v0 offset1:32
	v_mul_f32_e32 v0, v24, v143
	v_mul_f32_e32 v0, v0, v148
	v_add_u32_e32 v8, 0x6800, v153
	ds_write2_b32 v8, v6, v0 offset1:32
	v_mul_f32_e32 v0, v25, v144
	v_mul_f32_e32 v0, v0, v148
	v_add_u32_e32 v6, 0x6c00, v153
	ds_write2_b32 v6, v9, v0 offset1:32
	v_mul_f32_e32 v0, v32, v129
	v_mul_f32_e32 v32, v55, v129
	s_waitcnt vmcnt(5)
	v_mul_f32_e32 v0, v0, v145
	s_waitcnt vmcnt(4)
	v_mul_f32_e32 v32, v32, v146
	v_mul_f32_e32 v9, v33, v131
	ds_write2_b32 v153, v0, v32 offset0:64 offset1:96
	v_mul_f32_e32 v0, v54, v131
	v_mul_f32_e32 v9, v9, v145
	v_mul_f32_e32 v0, v0, v146
	v_mul_f32_e32 v16, v34, v133
	ds_write2_b32 v23, v9, v0 offset0:64 offset1:96
	v_mul_f32_e32 v0, v53, v133
	v_mul_f32_e32 v16, v16, v145
	v_mul_f32_e32 v0, v0, v146
	v_mul_f32_e32 v17, v35, v135
	ds_write2_b32 v21, v16, v0 offset0:64 offset1:96
	v_mul_f32_e32 v0, v52, v135
	v_mul_f32_e32 v17, v17, v145
	v_mul_f32_e32 v0, v0, v146
	v_mul_f32_e32 v18, v36, v137
	ds_write2_b32 v10, v17, v0 offset0:64 offset1:96
	v_mul_f32_e32 v0, v51, v137
	v_mul_f32_e32 v18, v18, v145
	v_mul_f32_e32 v0, v0, v146
	v_mul_f32_e32 v19, v37, v139
	ds_write2_b32 v7, v18, v0 offset0:64 offset1:96
	v_mul_f32_e32 v0, v50, v139
	v_mul_f32_e32 v19, v19, v145
	v_mul_f32_e32 v0, v0, v146
	v_mul_f32_e32 v20, v38, v141
	ds_write2_b32 v5, v19, v0 offset0:64 offset1:96
	v_mul_f32_e32 v0, v48, v141
	v_mul_f32_e32 v20, v20, v145
	v_mul_f32_e32 v0, v0, v146
	v_mul_f32_e32 v22, v39, v142
	ds_write2_b32 v4, v20, v0 offset0:64 offset1:96
	v_mul_f32_e32 v0, v49, v142
	v_mul_f32_e32 v22, v22, v145
	v_mul_f32_e32 v0, v0, v146
	v_mul_f32_e32 v24, v40, v140
	ds_write2_b32 v2, v22, v0 offset0:64 offset1:96
	v_mul_f32_e32 v0, v63, v140
	v_mul_f32_e32 v24, v24, v145
	v_mul_f32_e32 v0, v0, v146
	v_mul_f32_e32 v25, v41, v138
	ds_write2_b32 v3, v24, v0 offset0:64 offset1:96
	v_mul_f32_e32 v0, v62, v138
	v_mul_f32_e32 v25, v25, v145
	v_mul_f32_e32 v0, v0, v146
	v_mul_f32_e32 v26, v42, v136
	ds_write2_b32 v15, v25, v0 offset0:64 offset1:96
	v_mul_f32_e32 v0, v61, v136
	v_mul_f32_e32 v26, v26, v145
	v_mul_f32_e32 v0, v0, v146
	v_mul_f32_e32 v27, v43, v134
	ds_write2_b32 v14, v26, v0 offset0:64 offset1:96
	v_mul_f32_e32 v0, v60, v134
	v_mul_f32_e32 v27, v27, v145
	v_mul_f32_e32 v0, v0, v146
	v_mul_f32_e32 v28, v44, v132
	ds_write2_b32 v13, v27, v0 offset0:64 offset1:96
	v_mul_f32_e32 v0, v59, v132
	v_mul_f32_e32 v28, v28, v145
	v_mul_f32_e32 v0, v0, v146
	v_mul_f32_e32 v29, v45, v130
	ds_write2_b32 v12, v28, v0 offset0:64 offset1:96
	v_mul_f32_e32 v0, v58, v130
	v_mul_f32_e32 v29, v29, v145
	v_mul_f32_e32 v0, v0, v146
	v_mul_f32_e32 v30, v46, v143
	ds_write2_b32 v11, v29, v0 offset0:64 offset1:96
	v_mul_f32_e32 v0, v56, v143
	v_mul_f32_e32 v30, v30, v145
	v_mul_f32_e32 v0, v0, v146
	v_mul_f32_e32 v31, v47, v144
	ds_write2_b32 v8, v30, v0 offset0:64 offset1:96
	v_mul_f32_e32 v0, v57, v144
	v_mul_f32_e32 v31, v31, v145
	v_mul_f32_e32 v0, v0, v146
	ds_write2_b32 v6, v31, v0 offset0:64 offset1:96
	v_mul_f32_e32 v0, v64, v129
	v_mul_f32_e32 v32, v87, v129
	s_waitcnt vmcnt(3)
	v_mul_f32_e32 v0, v0, v147
	s_waitcnt vmcnt(2)
	v_mul_f32_e32 v32, v32, v150
	v_mul_f32_e32 v9, v65, v131
	ds_write2_b32 v153, v0, v32 offset0:128 offset1:160
	v_mul_f32_e32 v0, v86, v131
	v_mul_f32_e32 v9, v9, v147
	v_mul_f32_e32 v0, v0, v150
	v_mul_f32_e32 v16, v66, v133
	ds_write2_b32 v23, v9, v0 offset0:128 offset1:160
	v_mul_f32_e32 v0, v85, v133
	v_mul_f32_e32 v16, v16, v147
	v_mul_f32_e32 v0, v0, v150
	v_mul_f32_e32 v17, v67, v135
	ds_write2_b32 v21, v16, v0 offset0:128 offset1:160
	v_mul_f32_e32 v0, v84, v135
	v_mul_f32_e32 v17, v17, v147
	v_mul_f32_e32 v0, v0, v150
	v_mul_f32_e32 v18, v68, v137
	ds_write2_b32 v10, v17, v0 offset0:128 offset1:160
	v_mul_f32_e32 v0, v83, v137
	v_mul_f32_e32 v18, v18, v147
	v_mul_f32_e32 v0, v0, v150
	v_mul_f32_e32 v19, v69, v139
	ds_write2_b32 v7, v18, v0 offset0:128 offset1:160
	v_mul_f32_e32 v0, v82, v139
	v_mul_f32_e32 v19, v19, v147
	v_mul_f32_e32 v0, v0, v150
	v_mul_f32_e32 v20, v70, v141
	ds_write2_b32 v5, v19, v0 offset0:128 offset1:160
	v_mul_f32_e32 v0, v80, v141
	v_mul_f32_e32 v20, v20, v147
	v_mul_f32_e32 v0, v0, v150
	v_mul_f32_e32 v22, v71, v142
	ds_write2_b32 v4, v20, v0 offset0:128 offset1:160
	v_mul_f32_e32 v0, v81, v142
	v_mul_f32_e32 v22, v22, v147
	v_mul_f32_e32 v0, v0, v150
	v_mul_f32_e32 v24, v72, v140
	ds_write2_b32 v2, v22, v0 offset0:128 offset1:160
	v_mul_f32_e32 v0, v95, v140
	v_mul_f32_e32 v24, v24, v147
	v_mul_f32_e32 v0, v0, v150
	v_mul_f32_e32 v25, v73, v138
	ds_write2_b32 v3, v24, v0 offset0:128 offset1:160
	v_mul_f32_e32 v0, v94, v138
	v_mul_f32_e32 v25, v25, v147
	v_mul_f32_e32 v0, v0, v150
	v_mul_f32_e32 v26, v74, v136
	ds_write2_b32 v15, v25, v0 offset0:128 offset1:160
	v_mul_f32_e32 v0, v93, v136
	v_mul_f32_e32 v26, v26, v147
	v_mul_f32_e32 v0, v0, v150
	v_mul_f32_e32 v27, v75, v134
	ds_write2_b32 v14, v26, v0 offset0:128 offset1:160
	v_mul_f32_e32 v0, v92, v134
	v_mul_f32_e32 v27, v27, v147
	v_mul_f32_e32 v0, v0, v150
	v_mul_f32_e32 v28, v76, v132
	ds_write2_b32 v13, v27, v0 offset0:128 offset1:160
	v_mul_f32_e32 v0, v91, v132
	v_mul_f32_e32 v28, v28, v147
	v_mul_f32_e32 v0, v0, v150
	v_mul_f32_e32 v29, v77, v130
	ds_write2_b32 v12, v28, v0 offset0:128 offset1:160
	v_mul_f32_e32 v0, v90, v130
	v_mul_f32_e32 v29, v29, v147
	v_mul_f32_e32 v0, v0, v150
	v_mul_f32_e32 v30, v78, v143
	ds_write2_b32 v11, v29, v0 offset0:128 offset1:160
	v_mul_f32_e32 v0, v88, v143
	v_mul_f32_e32 v30, v30, v147
	v_mul_f32_e32 v0, v0, v150
	v_mul_f32_e32 v31, v79, v144
	ds_write2_b32 v8, v30, v0 offset0:128 offset1:160
	v_mul_f32_e32 v0, v89, v144
	v_mul_f32_e32 v31, v31, v147
	v_mul_f32_e32 v0, v0, v150
	ds_write2_b32 v6, v31, v0 offset0:128 offset1:160
	v_mul_f32_e32 v0, v96, v129
	v_mul_f32_e32 v32, v117, v129
	s_waitcnt vmcnt(1)
	v_mul_f32_e32 v0, v0, v151
	s_waitcnt vmcnt(0)
	v_mul_f32_e32 v32, v32, v152
	v_mul_f32_e32 v9, v97, v131
	ds_write2_b32 v153, v0, v32 offset0:192 offset1:224
	v_mul_f32_e32 v0, v116, v131
	v_mul_f32_e32 v9, v9, v151
	v_mul_f32_e32 v0, v0, v152
	v_mul_f32_e32 v16, v98, v133
	ds_write2_b32 v23, v9, v0 offset0:192 offset1:224
	v_mul_f32_e32 v0, v115, v133
	v_mul_f32_e32 v16, v16, v151
	v_mul_f32_e32 v0, v0, v152
	v_mul_f32_e32 v17, v99, v135
	ds_write2_b32 v21, v16, v0 offset0:192 offset1:224
	v_mul_f32_e32 v0, v114, v135
	v_mul_f32_e32 v17, v17, v151
	v_mul_f32_e32 v0, v0, v152
	v_mul_f32_e32 v18, v100, v137
	ds_write2_b32 v10, v17, v0 offset0:192 offset1:224
	v_mul_f32_e32 v0, v113, v137
	v_mul_f32_e32 v18, v18, v151
	v_mul_f32_e32 v0, v0, v152
	v_mul_f32_e32 v19, v101, v139
	ds_write2_b32 v7, v18, v0 offset0:192 offset1:224
	v_mul_f32_e32 v0, v119, v139
	v_mul_f32_e32 v19, v19, v151
	v_mul_f32_e32 v0, v0, v152
	v_mul_f32_e32 v20, v102, v141
	ds_write2_b32 v5, v19, v0 offset0:192 offset1:224
	v_mul_f32_e32 v0, v118, v141
	v_mul_f32_e32 v20, v20, v151
	v_mul_f32_e32 v0, v0, v152
	v_mul_f32_e32 v22, v103, v142
	ds_write2_b32 v4, v20, v0 offset0:192 offset1:224
	v_mul_f32_e32 v0, v120, v142
	v_mul_f32_e32 v22, v22, v151
	v_mul_f32_e32 v0, v0, v152
	v_mul_f32_e32 v24, v104, v140
	ds_write2_b32 v2, v22, v0 offset0:192 offset1:224
	v_mul_f32_e32 v0, v121, v140
	v_mul_f32_e32 v24, v24, v151
	v_mul_f32_e32 v0, v0, v152
	v_mul_f32_e32 v25, v105, v138
	ds_write2_b32 v3, v24, v0 offset0:192 offset1:224
	v_mul_f32_e32 v0, v124, v138
	v_mul_f32_e32 v25, v25, v151
	v_mul_f32_e32 v0, v0, v152
	v_mul_f32_e32 v26, v106, v136
	ds_write2_b32 v15, v25, v0 offset0:192 offset1:224
	v_mul_f32_e32 v0, v122, v136
	v_mul_f32_e32 v26, v26, v151
	v_mul_f32_e32 v0, v0, v152
	v_mul_f32_e32 v27, v107, v134
	ds_write2_b32 v14, v26, v0 offset0:192 offset1:224
	v_mul_f32_e32 v0, v125, v134
	v_mul_f32_e32 v27, v27, v151
	v_mul_f32_e32 v0, v0, v152
	v_mul_f32_e32 v28, v108, v132
	ds_write2_b32 v13, v27, v0 offset0:192 offset1:224
	v_mul_f32_e32 v0, v123, v132
	v_mul_f32_e32 v28, v28, v151
	v_mul_f32_e32 v0, v0, v152
	v_mul_f32_e32 v29, v109, v130
	ds_write2_b32 v12, v28, v0 offset0:192 offset1:224
	v_mul_f32_e32 v0, v127, v130
	v_mul_f32_e32 v29, v29, v151
	v_mul_f32_e32 v0, v0, v152
	v_mul_f32_e32 v30, v110, v143
	ds_write2_b32 v11, v29, v0 offset0:192 offset1:224
	v_mul_f32_e32 v0, v126, v143
	v_mul_f32_e32 v30, v30, v151
	v_mul_f32_e32 v0, v0, v152
	v_mul_f32_e32 v31, v111, v144
	ds_write2_b32 v8, v30, v0 offset0:192 offset1:224
	v_mul_f32_e32 v0, v128, v144
	v_mul_f32_e32 v31, v31, v151
	v_mul_f32_e32 v0, v0, v152
	ds_write2_b32 v6, v31, v0 offset0:192 offset1:224
	v_mov_b32_e32 v0, v220
	s_mov_b64 s[2:3], 0
	v_ashrrev_i32_e32 v4, 5, v0
	v_ashrrev_i32_e32 v5, 31, v4
	v_lshl_add_u64 v[2:3], v[4:5], 0, s[4:5]
	v_lshlrev_b32_e32 v5, 4, v0
	v_lshlrev_b64 v[2:3], 12, v[2:3]
	v_and_b32_e32 v5, 0x1f0, v5
	v_and_b32_e32 v0, 31, v0
	v_or3_b32 v2, s0, v5, v2
	v_lshl_add_u32 v4, v4, 10, s36
	v_lshlrev_b32_e32 v0, 5, v0
	v_lshl_add_u64 v[2:3], s[80:81], 0, v[2:3]
	v_add3_u32 v0, v4, v0, 0
